# GEMM K-loops: removed the no-op s_setprio 0/1 pair inside each 32-MFMA block and the redundant lgkmcnt(0) after the barrier
# baseline (speedup 1.0000x reference)
; #define PG8_STAGE(bufoff, gbase, voff) do { _Pragma("unroll") for (int _i = 0; _i < 2; ++_i) \
;         __builtin_amdgcn_global_load_lds((const unsigned*)((const char*)(gbase) + (voff)[_i]), (PG8_LAS unsigned*)(lds + (bufoff) + ldsw + _i * 8192), 16, 0, 0); } while (0)
; #define PG8_LDA(dst, b, h) do { _Pragma("unroll") for (int m = 0; m < 4; ++m) _Pragma("unroll") for (int k = 0; k < 2; ++k) dst[m][k] = *(const PG8_LAS bf16x8*)(lds + PG8_SA(b, h) + aoff + m * 2048 + k * 1024); } while (0)
; #define PG8_LDB(dst, b, h) do { _Pragma("unroll") for (int n = 0; n < 2; ++n) _Pragma("unroll") for (int k = 0; k < 2; ++k) dst[n][k] = *(const PG8_LAS bf16x8*)(lds + PG8_SB(b, h) + boff + n * 2048 + k * 1024); } while (0)
; #define PG8_MMA(ai, bj, At, Bt) do { __builtin_amdgcn_s_setprio(1); _Pragma("unroll") for (int m = 0; m < 4; ++m) _Pragma("unroll") for (int n = 0; n < 2; ++n) _Pragma("unroll") for (int k = 0; k < 2; ++k) \
;         acc[ai][bj][m][n] = __builtin_amdgcn_mfma_f32_16x16x32_bf16(Bt[n][k], At[m][k], acc[ai][bj][m][n], 0, 0, 0); __builtin_amdgcn_s_setprio(0); } while (0)
; #define PG8_WAIT_V(n) asm volatile("s_waitcnt vmcnt(" #n ")" ::: "memory")
; #define PG8_WAIT_L(n) asm volatile("s_waitcnt lgkmcnt(" #n ")" ::: "memory")
; #define PG8_BAR __builtin_amdgcn_s_barrier()
; #define PG8_SCHED __builtin_amdgcn_sched_barrier(0)
; template <class Epi, class Sched, bool ALIGN_EPI = false, bool SP2 = false>
; __device__ __forceinline__ void gemm_phase(PG8_LAS unsigned char* lds, const Gemm g, const Sched& S, const Epi& E) {
;     ...
;             const char* a1 = cA + (size_t)(t + 1) * kstep;
;             const char* a2 = last ? nA : cA + (size_t)(t + 2) * kstep; const char* b2 = last ? nB : cB + (size_t)(t + 2) * kstep;
;             const char* a3 = a2 + kstep; const char* b3 = b2 + kstep;
;             if (last && has_next) S.a_ready(nxt);
;             if constexpr (SP2) {
;             PG8_LDB(B0, 0, 0); PG8_LDB(B1, 0, 1); PG8_SCHED; PG8_LDA(At, 0, 0); PG8_STAGE(PG8_SA(1, 1), a1 + hstep, voffA);
;             PG8_WAIT_V(8); PG8_WAIT_L(0); PG8_BAR; PG8_MMA(0, 0, At, B0); PG8_MMA(0, 1, At, B1); PG8_BAR; PG8_SCHED;
;             PG8_LDA(At, 0, 1); PG8_STAGE(PG8_SB(0, 0), b2, voffB); PG8_STAGE(PG8_SB(0, 1), b2 + hstep, voffB); PG8_STAGE(PG8_SA(0, 0), a2, voffA);
.LBB0_424:
	s_add_u32 s66, s8, 0xfff80080
	s_addc_u32 s67, s9, -1
	s_add_i32 s72, 0, 0x10000
	s_cmp_eq_u32 s29, 28
	s_cselect_b32 s97, s14, s67
	s_cselect_b32 s96, s15, s66
	v_add_u32_e32 v128, s72, v187
	s_cselect_b32 s67, s16, s19
	s_cselect_b32 s66, s17, s18
	s_add_i32 s90, 0, 0x14000
	ds_read_b128 v[134:137], v128
	ds_read_b128 v[138:141], v128 offset:1024
	ds_read_b128 v[142:145], v128 offset:2048
	ds_read_b128 v[166:169], v128 offset:3072
	v_add_u32_e32 v128, s90, v187
	ds_read_b128 v[170:173], v128
	ds_read_b128 v[174:177], v128 offset:1024
	ds_read_b128 v[178:181], v128 offset:2048
	ds_read_b128 v[182:185], v128 offset:3072
	v_lshl_add_u64 v[222:223], s[8:9], 0, v[158:159]
	s_add_i32 m0, s13, 0xc000
	ds_read_b128 v[190:193], v189
	ds_read_b128 v[194:197], v189 offset:1024
	ds_read_b128 v[198:201], v189 offset:2048
	ds_read_b128 v[202:205], v189 offset:3072
	ds_read_b128 v[206:209], v189 offset:4096
	ds_read_b128 v[210:213], v189 offset:5120
	ds_read_b128 v[214:217], v189 offset:6144
	ds_read_b128 v[218:221], v189 offset:7168
	global_load_lds_dwordx4 v[222:223], off
	v_lshl_add_u64 v[222:223], s[8:9], 0, v[156:157]
	s_add_i32 m0, s13, 0xe000
	s_nop 0
	global_load_lds_dwordx4 v[222:223], off
	s_waitcnt vmcnt(8)
	s_waitcnt lgkmcnt(0)
	s_barrier
	s_setprio 1
	v_mfma_f32_16x16x32_bf16 v[130:133], v[134:137], v[190:193], v[130:133]
	v_mfma_f32_16x16x32_bf16 v[124:127], v[142:145], v[190:193], v[124:127]
	v_mfma_f32_16x16x32_bf16 v[116:119], v[134:137], v[198:201], v[116:119]
	v_mfma_f32_16x16x32_bf16 v[108:111], v[142:145], v[198:201], v[108:111]
	v_mfma_f32_16x16x32_bf16 v[100:103], v[134:137], v[206:209], v[100:103]
	v_mfma_f32_16x16x32_bf16 v[92:95], v[142:145], v[206:209], v[92:95]
	v_mfma_f32_16x16x32_bf16 v[84:87], v[134:137], v[214:217], v[84:87]
	v_mfma_f32_16x16x32_bf16 v[76:79], v[142:145], v[214:217], v[76:79]
	v_mfma_f32_16x16x32_bf16 v[130:133], v[138:141], v[194:197], v[130:133]
	v_mfma_f32_16x16x32_bf16 v[124:127], v[166:169], v[194:197], v[124:127]
	v_mfma_f32_16x16x32_bf16 v[116:119], v[138:141], v[202:205], v[116:119]
	v_mfma_f32_16x16x32_bf16 v[108:111], v[166:169], v[202:205], v[108:111]
	v_mfma_f32_16x16x32_bf16 v[100:103], v[138:141], v[210:213], v[100:103]
	v_mfma_f32_16x16x32_bf16 v[92:95], v[166:169], v[210:213], v[92:95]
	v_mfma_f32_16x16x32_bf16 v[84:87], v[138:141], v[218:221], v[84:87]
	v_mfma_f32_16x16x32_bf16 v[76:79], v[166:169], v[218:221], v[76:79]
	v_mfma_f32_16x16x32_bf16 v[120:123], v[170:173], v[190:193], v[120:123]
	v_mfma_f32_16x16x32_bf16 v[112:115], v[178:181], v[190:193], v[112:115]
	v_mfma_f32_16x16x32_bf16 v[104:107], v[170:173], v[198:201], v[104:107]
	v_mfma_f32_16x16x32_bf16 v[96:99], v[178:181], v[198:201], v[96:99]
	v_mfma_f32_16x16x32_bf16 v[88:91], v[170:173], v[206:209], v[88:91]
	v_mfma_f32_16x16x32_bf16 v[80:83], v[178:181], v[206:209], v[80:83]
	v_mfma_f32_16x16x32_bf16 v[72:75], v[170:173], v[214:217], v[72:75]
	v_mfma_f32_16x16x32_bf16 v[68:71], v[178:181], v[214:217], v[68:71]
	v_mfma_f32_16x16x32_bf16 v[120:123], v[174:177], v[194:197], v[120:123]
	v_mfma_f32_16x16x32_bf16 v[112:115], v[182:185], v[194:197], v[112:115]
	v_mfma_f32_16x16x32_bf16 v[104:107], v[174:177], v[202:205], v[104:107]
	v_mfma_f32_16x16x32_bf16 v[96:99], v[182:185], v[202:205], v[96:99]
	v_mfma_f32_16x16x32_bf16 v[88:91], v[174:177], v[210:213], v[88:91]
	v_mfma_f32_16x16x32_bf16 v[80:83], v[182:185], v[210:213], v[80:83]
	v_mfma_f32_16x16x32_bf16 v[72:75], v[174:177], v[218:221], v[72:75]
	v_mfma_f32_16x16x32_bf16 v[68:71], v[182:185], v[218:221], v[68:71]
	s_setprio 0
	s_barrier
	s_add_i32 s72, s72, s20
	v_lshl_add_u64 v[222:223], s[66:67], 0, v[150:151]
	s_mov_b32 m0, s72
	ds_read_b128 v[190:193], v189 offset:16384
	ds_read_b128 v[194:197], v189 offset:17408
	ds_read_b128 v[198:201], v189 offset:18432
	ds_read_b128 v[202:205], v189 offset:19456
	ds_read_b128 v[206:209], v189 offset:20480
	ds_read_b128 v[210:213], v189 offset:21504
	ds_read_b128 v[214:217], v189 offset:22528
	ds_read_b128 v[218:221], v189 offset:23552
	global_load_lds_dwordx4 v[222:223], off
	s_add_i32 m0, s72, 0x2000
	s_add_u32 s72, s66, 0x80000
	v_lshl_add_u64 v[224:225], s[66:67], 0, v[146:147]
	s_addc_u32 s73, s67, 0
	s_add_i32 s90, s90, s20
	global_load_lds_dwordx4 v[224:225], off
	v_lshl_add_u64 v[226:227], s[72:73], 0, v[150:151]
	s_mov_b32 m0, s90
	v_lshl_add_u64 v[228:229], s[96:97], 0, v[148:149]
	global_load_lds_dwordx4 v[226:227], off
	v_lshl_add_u64 v[226:227], s[72:73], 0, v[146:147]
	s_add_i32 m0, s90, 0x2000
	s_nop 0
	global_load_lds_dwordx4 v[226:227], off
	v_lshl_add_u64 v[226:227], s[96:97], 0, v[152:153]
	s_mov_b32 m0, s13
	s_nop 0
	global_load_lds_dwordx4 v[226:227], off
	s_mov_b32 m0, s23
	s_nop 0
	global_load_lds_dwordx4 v[228:229], off
	s_waitcnt vmcnt(8)
	s_waitcnt lgkmcnt(0)
	s_barrier
; #define PG8_STAGE(bufoff, gbase, voff) do { _Pragma("unroll") for (int _i = 0; _i < 2; ++_i) \
;         __builtin_amdgcn_global_load_lds((const unsigned*)((const char*)(gbase) + (voff)[_i]), (PG8_LAS unsigned*)(lds + (bufoff) + ldsw + _i * 8192), 16, 0, 0); } while (0)
; #define PG8_LDA(dst, b, h) do { _Pragma("unroll") for (int m = 0; m < 4; ++m) _Pragma("unroll") for (int k = 0; k < 2; ++k) dst[m][k] = *(const PG8_LAS bf16x8*)(lds + PG8_SA(b, h) + aoff + m * 2048 + k * 1024); } while (0)
; #define PG8_LDB(dst, b, h) do { _Pragma("unroll") for (int n = 0; n < 2; ++n) _Pragma("unroll") for (int k = 0; k < 2; ++k) dst[n][k] = *(const PG8_LAS bf16x8*)(lds + PG8_SB(b, h) + boff + n * 2048 + k * 1024); } while (0)
; #define PG8_MMA(ai, bj, At, Bt) do { __builtin_amdgcn_s_setprio(1); _Pragma("unroll") for (int m = 0; m < 4; ++m) _Pragma("unroll") for (int n = 0; n < 2; ++n) _Pragma("unroll") for (int k = 0; k < 2; ++k) \
;         acc[ai][bj][m][n] = __builtin_amdgcn_mfma_f32_16x16x32_bf16(Bt[n][k], At[m][k], acc[ai][bj][m][n], 0, 0, 0); __builtin_amdgcn_s_setprio(0); } while (0)
; #define PG8_WAIT_V(n) asm volatile("s_waitcnt vmcnt(" #n ")" ::: "memory")
; #define PG8_WAIT_L(n) asm volatile("s_waitcnt lgkmcnt(" #n ")" ::: "memory")
; #define PG8_BAR __builtin_amdgcn_s_barrier()
; #define PG8_SCHED __builtin_amdgcn_sched_barrier(0)
; template <class Epi, class Sched, bool ALIGN_EPI = false, bool SP2 = false>
; __device__ __forceinline__ void gemm_phase(PG8_LAS unsigned char* lds, const Gemm g, const Sched& S, const Epi& E) {
;     ...
;             PG8_LDA(At, 0, 1); PG8_STAGE(PG8_SB(0, 0), b2, voffB); PG8_STAGE(PG8_SB(0, 1), b2 + hstep, voffB); PG8_STAGE(PG8_SA(0, 0), a2, voffA);
;             PG8_WAIT_V(8); PG8_WAIT_L(0); PG8_BAR; PG8_MMA(1, 0, At, B0); PG8_MMA(1, 1, At, B1); PG8_BAR; PG8_SCHED;
;             PG8_LDB(B0, 1, 0); PG8_LDB(B1, 1, 1); PG8_SCHED; PG8_LDA(At, 1, 0); PG8_STAGE(PG8_SA(0, 1), a2 + hstep, voffA);
;             PG8_WAIT_V(8); PG8_WAIT_L(0); PG8_BAR; PG8_MMA(0, 0, At, B0); PG8_MMA(0, 1, At, B1); PG8_BAR; PG8_SCHED;
;             PG8_LDA(At, 1, 1); PG8_STAGE(PG8_SB(1, 0), b3, voffB); PG8_STAGE(PG8_SB(1, 1), b3 + hstep, voffB); PG8_STAGE(PG8_SA(1, 0), a3, voffA);
	s_setprio 1
	v_mfma_f32_16x16x32_bf16 v[64:67], v[134:137], v[190:193], v[64:67]
	v_mfma_f32_16x16x32_bf16 v[60:63], v[142:145], v[190:193], v[60:63]
	v_mfma_f32_16x16x32_bf16 v[52:55], v[134:137], v[198:201], v[52:55]
	v_mfma_f32_16x16x32_bf16 v[44:47], v[142:145], v[198:201], v[44:47]
	v_mfma_f32_16x16x32_bf16 v[32:35], v[134:137], v[206:209], v[32:35]
	v_mfma_f32_16x16x32_bf16 v[24:27], v[142:145], v[206:209], v[24:27]
	v_mfma_f32_16x16x32_bf16 v[16:19], v[134:137], v[214:217], v[16:19]
	v_mfma_f32_16x16x32_bf16 v[8:11], v[142:145], v[214:217], v[8:11]
	v_mfma_f32_16x16x32_bf16 v[64:67], v[138:141], v[194:197], v[64:67]
	v_mfma_f32_16x16x32_bf16 v[60:63], v[166:169], v[194:197], v[60:63]
	v_mfma_f32_16x16x32_bf16 v[52:55], v[138:141], v[202:205], v[52:55]
	v_mfma_f32_16x16x32_bf16 v[44:47], v[166:169], v[202:205], v[44:47]
	v_mfma_f32_16x16x32_bf16 v[32:35], v[138:141], v[210:213], v[32:35]
	v_mfma_f32_16x16x32_bf16 v[24:27], v[166:169], v[210:213], v[24:27]
	v_mfma_f32_16x16x32_bf16 v[16:19], v[138:141], v[218:221], v[16:19]
	v_mfma_f32_16x16x32_bf16 v[8:11], v[166:169], v[218:221], v[8:11]
	v_mfma_f32_16x16x32_bf16 v[56:59], v[170:173], v[190:193], v[56:59]
	v_mfma_f32_16x16x32_bf16 v[48:51], v[178:181], v[190:193], v[48:51]
	v_mfma_f32_16x16x32_bf16 v[36:39], v[170:173], v[198:201], v[36:39]
	v_mfma_f32_16x16x32_bf16 v[28:31], v[178:181], v[198:201], v[28:31]
	v_mfma_f32_16x16x32_bf16 v[20:23], v[170:173], v[206:209], v[20:23]
	v_mfma_f32_16x16x32_bf16 v[12:15], v[178:181], v[206:209], v[12:15]
	v_mfma_f32_16x16x32_bf16 v[4:7], v[170:173], v[214:217], v[4:7]
	v_mfma_f32_16x16x32_bf16 v[0:3], v[178:181], v[214:217], v[0:3]
	v_mfma_f32_16x16x32_bf16 v[56:59], v[174:177], v[194:197], v[56:59]
	v_mfma_f32_16x16x32_bf16 v[48:51], v[182:185], v[194:197], v[48:51]
	v_mfma_f32_16x16x32_bf16 v[36:39], v[174:177], v[202:205], v[36:39]
	v_mfma_f32_16x16x32_bf16 v[28:31], v[182:185], v[202:205], v[28:31]
	v_mfma_f32_16x16x32_bf16 v[20:23], v[174:177], v[210:213], v[20:23]
	v_mfma_f32_16x16x32_bf16 v[12:15], v[182:185], v[210:213], v[12:15]
	v_mfma_f32_16x16x32_bf16 v[4:7], v[174:177], v[218:221], v[4:7]
	v_mfma_f32_16x16x32_bf16 v[0:3], v[182:185], v[218:221], v[0:3]
	s_setprio 0
	s_barrier
	s_add_i32 s90, 0, 0x18000
	v_add_u32_e32 v128, s90, v187
	s_add_i32 s91, 0, 0x1c000
	ds_read_b128 v[134:137], v128
	ds_read_b128 v[138:141], v128 offset:1024
	ds_read_b128 v[142:145], v128 offset:2048
	ds_read_b128 v[166:169], v128 offset:3072
	v_add_u32_e32 v128, s91, v187
	ds_read_b128 v[170:173], v128
	ds_read_b128 v[174:177], v128 offset:1024
	ds_read_b128 v[178:181], v128 offset:2048
	ds_read_b128 v[182:185], v128 offset:3072
	s_add_u32 s72, s96, 0x80000
	s_addc_u32 s73, s97, 0
	s_mov_b32 m0, s24
	v_lshl_add_u64 v[230:231], s[72:73], 0, v[152:153]
	ds_read_b128 v[190:193], v189 offset:32768
	ds_read_b128 v[194:197], v189 offset:33792
	ds_read_b128 v[198:201], v189 offset:34816
	ds_read_b128 v[202:205], v189 offset:35840
	ds_read_b128 v[206:209], v189 offset:36864
	ds_read_b128 v[210:213], v189 offset:37888
	ds_read_b128 v[214:217], v189 offset:38912
	ds_read_b128 v[218:221], v189 offset:39936
	global_load_lds_dwordx4 v[230:231], off
	v_lshl_add_u64 v[230:231], s[72:73], 0, v[148:149]
	s_mov_b32 m0, s25
	s_nop 0
	global_load_lds_dwordx4 v[230:231], off
	s_waitcnt vmcnt(8)
	s_waitcnt lgkmcnt(0)
	s_barrier
	s_setprio 1
	v_mfma_f32_16x16x32_bf16 v[130:133], v[134:137], v[190:193], v[130:133]
	v_mfma_f32_16x16x32_bf16 v[124:127], v[142:145], v[190:193], v[124:127]
	v_mfma_f32_16x16x32_bf16 v[116:119], v[134:137], v[198:201], v[116:119]
	v_mfma_f32_16x16x32_bf16 v[108:111], v[142:145], v[198:201], v[108:111]
	v_mfma_f32_16x16x32_bf16 v[100:103], v[134:137], v[206:209], v[100:103]
	v_mfma_f32_16x16x32_bf16 v[92:95], v[142:145], v[206:209], v[92:95]
	v_mfma_f32_16x16x32_bf16 v[84:87], v[134:137], v[214:217], v[84:87]
	v_mfma_f32_16x16x32_bf16 v[76:79], v[142:145], v[214:217], v[76:79]
	v_mfma_f32_16x16x32_bf16 v[130:133], v[138:141], v[194:197], v[130:133]
	v_mfma_f32_16x16x32_bf16 v[124:127], v[166:169], v[194:197], v[124:127]
	v_mfma_f32_16x16x32_bf16 v[116:119], v[138:141], v[202:205], v[116:119]
	v_mfma_f32_16x16x32_bf16 v[108:111], v[166:169], v[202:205], v[108:111]
	v_mfma_f32_16x16x32_bf16 v[100:103], v[138:141], v[210:213], v[100:103]
	v_mfma_f32_16x16x32_bf16 v[92:95], v[166:169], v[210:213], v[92:95]
	v_mfma_f32_16x16x32_bf16 v[84:87], v[138:141], v[218:221], v[84:87]
	v_mfma_f32_16x16x32_bf16 v[76:79], v[166:169], v[218:221], v[76:79]
	v_mfma_f32_16x16x32_bf16 v[120:123], v[170:173], v[190:193], v[120:123]
	v_mfma_f32_16x16x32_bf16 v[112:115], v[178:181], v[190:193], v[112:115]
	v_mfma_f32_16x16x32_bf16 v[104:107], v[170:173], v[198:201], v[104:107]
	v_mfma_f32_16x16x32_bf16 v[96:99], v[178:181], v[198:201], v[96:99]
	v_mfma_f32_16x16x32_bf16 v[88:91], v[170:173], v[206:209], v[88:91]
	v_mfma_f32_16x16x32_bf16 v[80:83], v[178:181], v[206:209], v[80:83]
	v_mfma_f32_16x16x32_bf16 v[72:75], v[170:173], v[214:217], v[72:75]
	v_mfma_f32_16x16x32_bf16 v[68:71], v[178:181], v[214:217], v[68:71]
	v_mfma_f32_16x16x32_bf16 v[120:123], v[174:177], v[194:197], v[120:123]
	v_mfma_f32_16x16x32_bf16 v[112:115], v[182:185], v[194:197], v[112:115]
	v_mfma_f32_16x16x32_bf16 v[104:107], v[174:177], v[202:205], v[104:107]
	v_mfma_f32_16x16x32_bf16 v[96:99], v[182:185], v[202:205], v[96:99]
	v_mfma_f32_16x16x32_bf16 v[88:91], v[174:177], v[210:213], v[88:91]
	v_mfma_f32_16x16x32_bf16 v[80:83], v[182:185], v[210:213], v[80:83]
	v_mfma_f32_16x16x32_bf16 v[72:75], v[174:177], v[218:221], v[72:75]
	v_mfma_f32_16x16x32_bf16 v[68:71], v[182:185], v[218:221], v[68:71]
	s_setprio 0
	s_barrier
; #define PG8_STAGE(bufoff, gbase, voff) do { _Pragma("unroll") for (int _i = 0; _i < 2; ++_i) \
;         __builtin_amdgcn_global_load_lds((const unsigned*)((const char*)(gbase) + (voff)[_i]), (PG8_LAS unsigned*)(lds + (bufoff) + ldsw + _i * 8192), 16, 0, 0); } while (0)
; #define PG8_LDA(dst, b, h) do { _Pragma("unroll") for (int m = 0; m < 4; ++m) _Pragma("unroll") for (int k = 0; k < 2; ++k) dst[m][k] = *(const PG8_LAS bf16x8*)(lds + PG8_SA(b, h) + aoff + m * 2048 + k * 1024); } while (0)
; #define PG8_MMA(ai, bj, At, Bt) do { __builtin_amdgcn_s_setprio(1); _Pragma("unroll") for (int m = 0; m < 4; ++m) _Pragma("unroll") for (int n = 0; n < 2; ++n) _Pragma("unroll") for (int k = 0; k < 2; ++k) \
;         acc[ai][bj][m][n] = __builtin_amdgcn_mfma_f32_16x16x32_bf16(Bt[n][k], At[m][k], acc[ai][bj][m][n], 0, 0, 0); __builtin_amdgcn_s_setprio(0); } while (0)
; #define PG8_WAIT_V(n) asm volatile("s_waitcnt vmcnt(" #n ")" ::: "memory")
; #define PG8_WAIT_L(n) asm volatile("s_waitcnt lgkmcnt(" #n ")" ::: "memory")
; #define PG8_BAR __builtin_amdgcn_s_barrier()
; #define PG8_SCHED __builtin_amdgcn_sched_barrier(0)
; template <class Epi, class Sched, bool ALIGN_EPI = false, bool SP2 = false>
; __device__ __forceinline__ void gemm_phase(PG8_LAS unsigned char* lds, const Gemm g, const Sched& S, const Epi& E) {
;     ...
;             PG8_LDA(At, 1, 1); PG8_STAGE(PG8_SB(1, 0), b3, voffB); PG8_STAGE(PG8_SB(1, 1), b3 + hstep, voffB); PG8_STAGE(PG8_SA(1, 0), a3, voffA);
;             PG8_WAIT_V(8); PG8_WAIT_L(0); PG8_BAR; PG8_MMA(1, 0, At, B0); PG8_MMA(1, 1, At, B1); PG8_BAR; PG8_SCHED;
;     ...
;         if constexpr (ALIGN_EPI) { if (wr == 0) PG8_BAR; }
	s_add_i32 s72, s90, s20
	v_lshl_add_u64 v[222:223], v[222:223], 0, s[76:77]
	s_mov_b32 m0, s72
	ds_read_b128 v[190:193], v189 offset:49152
	ds_read_b128 v[194:197], v189 offset:50176
	ds_read_b128 v[198:201], v189 offset:51200
	ds_read_b128 v[202:205], v189 offset:52224
	ds_read_b128 v[206:209], v189 offset:53248
	ds_read_b128 v[210:213], v189 offset:54272
	ds_read_b128 v[214:217], v189 offset:55296
	ds_read_b128 v[218:221], v189 offset:56320
	global_load_lds_dwordx4 v[222:223], off
	s_add_i32 m0, s72, 0x2000
	s_add_u32 s66, s66, 0x80080
	v_lshl_add_u64 v[222:223], v[224:225], 0, s[76:77]
	s_addc_u32 s67, s67, 0
	s_add_i32 s72, s91, s20
	global_load_lds_dwordx4 v[222:223], off
	v_lshl_add_u64 v[222:223], s[66:67], 0, v[150:151]
	s_mov_b32 m0, s72
	s_nop 0
	global_load_lds_dwordx4 v[222:223], off
	v_lshl_add_u64 v[222:223], s[66:67], 0, v[146:147]
	s_add_i32 m0, s72, 0x2000
	s_nop 0
	global_load_lds_dwordx4 v[222:223], off
	v_lshl_add_u64 v[222:223], v[226:227], 0, s[76:77]
	s_mov_b32 m0, s26
	s_nop 0
	global_load_lds_dwordx4 v[222:223], off
	v_lshl_add_u64 v[222:223], v[228:229], 0, s[76:77]
	s_mov_b32 m0, s27
	s_nop 0
	global_load_lds_dwordx4 v[222:223], off
	s_waitcnt vmcnt(8)
	s_waitcnt lgkmcnt(0)
	s_barrier
	s_setprio 1
	v_mfma_f32_16x16x32_bf16 v[64:67], v[134:137], v[190:193], v[64:67]
	v_mfma_f32_16x16x32_bf16 v[60:63], v[142:145], v[190:193], v[60:63]
	v_mfma_f32_16x16x32_bf16 v[52:55], v[134:137], v[198:201], v[52:55]
	v_mfma_f32_16x16x32_bf16 v[44:47], v[142:145], v[198:201], v[44:47]
	v_mfma_f32_16x16x32_bf16 v[32:35], v[134:137], v[206:209], v[32:35]
	v_mfma_f32_16x16x32_bf16 v[24:27], v[142:145], v[206:209], v[24:27]
	v_mfma_f32_16x16x32_bf16 v[16:19], v[134:137], v[214:217], v[16:19]
	v_mfma_f32_16x16x32_bf16 v[8:11], v[142:145], v[214:217], v[8:11]
	v_mfma_f32_16x16x32_bf16 v[64:67], v[138:141], v[194:197], v[64:67]
	v_mfma_f32_16x16x32_bf16 v[60:63], v[166:169], v[194:197], v[60:63]
	v_mfma_f32_16x16x32_bf16 v[52:55], v[138:141], v[202:205], v[52:55]
	v_mfma_f32_16x16x32_bf16 v[44:47], v[166:169], v[202:205], v[44:47]
	v_mfma_f32_16x16x32_bf16 v[32:35], v[138:141], v[210:213], v[32:35]
	v_mfma_f32_16x16x32_bf16 v[24:27], v[166:169], v[210:213], v[24:27]
	v_mfma_f32_16x16x32_bf16 v[16:19], v[138:141], v[218:221], v[16:19]
	v_mfma_f32_16x16x32_bf16 v[8:11], v[166:169], v[218:221], v[8:11]
	v_mfma_f32_16x16x32_bf16 v[56:59], v[170:173], v[190:193], v[56:59]
	v_mfma_f32_16x16x32_bf16 v[48:51], v[178:181], v[190:193], v[48:51]
	v_mfma_f32_16x16x32_bf16 v[36:39], v[170:173], v[198:201], v[36:39]
	v_mfma_f32_16x16x32_bf16 v[28:31], v[178:181], v[198:201], v[28:31]
	v_mfma_f32_16x16x32_bf16 v[20:23], v[170:173], v[206:209], v[20:23]
	v_mfma_f32_16x16x32_bf16 v[12:15], v[178:181], v[206:209], v[12:15]
	v_mfma_f32_16x16x32_bf16 v[4:7], v[170:173], v[214:217], v[4:7]
	v_mfma_f32_16x16x32_bf16 v[0:3], v[178:181], v[214:217], v[0:3]
	v_mfma_f32_16x16x32_bf16 v[56:59], v[174:177], v[194:197], v[56:59]
	v_mfma_f32_16x16x32_bf16 v[48:51], v[182:185], v[194:197], v[48:51]
	v_mfma_f32_16x16x32_bf16 v[36:39], v[174:177], v[202:205], v[36:39]
	v_mfma_f32_16x16x32_bf16 v[28:31], v[182:185], v[202:205], v[28:31]
	v_mfma_f32_16x16x32_bf16 v[20:23], v[174:177], v[210:213], v[20:23]
	v_mfma_f32_16x16x32_bf16 v[12:15], v[182:185], v[210:213], v[12:15]
	v_mfma_f32_16x16x32_bf16 v[4:7], v[174:177], v[218:221], v[4:7]
	v_mfma_f32_16x16x32_bf16 v[0:3], v[182:185], v[218:221], v[0:3]
	s_setprio 0
	s_barrier
	s_add_i32 s29, s29, 2
	s_add_u32 s18, s18, 0x100
	s_addc_u32 s19, s19, 0
	s_add_u32 s8, s8, 0x100
	s_addc_u32 s9, s9, 0
	s_cmp_gt_u32 s29, 29
	s_cbranch_scc0 .LBB0_424
	s_and_b64 vcc, exec, s[70:71]
	s_cbranch_vccz .LBB0_427
	s_barrier

; #define PG8_STAGE(bufoff, gbase, voff) do { _Pragma("unroll") for (int _i = 0; _i < 2; ++_i) \
;         __builtin_amdgcn_global_load_lds((const unsigned*)((const char*)(gbase) + (voff)[_i]), (PG8_LAS unsigned*)(lds + (bufoff) + ldsw + _i * 8192), 16, 0, 0); } while (0)
; #define PG8_LDA(dst, b, h) do { _Pragma("unroll") for (int m = 0; m < 4; ++m) _Pragma("unroll") for (int k = 0; k < 2; ++k) dst[m][k] = *(const PG8_LAS bf16x8*)(lds + PG8_SA(b, h) + aoff + m * 2048 + k * 1024); } while (0)
; #define PG8_LDB(dst, b, h) do { _Pragma("unroll") for (int n = 0; n < 2; ++n) _Pragma("unroll") for (int k = 0; k < 2; ++k) dst[n][k] = *(const PG8_LAS bf16x8*)(lds + PG8_SB(b, h) + boff + n * 2048 + k * 1024); } while (0)
; #define PG8_MMA(ai, bj, At, Bt) do { __builtin_amdgcn_s_setprio(1); _Pragma("unroll") for (int m = 0; m < 4; ++m) _Pragma("unroll") for (int n = 0; n < 2; ++n) _Pragma("unroll") for (int k = 0; k < 2; ++k) \
;         acc[ai][bj][m][n] = __builtin_amdgcn_mfma_f32_16x16x32_bf16(Bt[n][k], At[m][k], acc[ai][bj][m][n], 0, 0, 0); __builtin_amdgcn_s_setprio(0); } while (0)
; #define PG8_WAIT_V(n) asm volatile("s_waitcnt vmcnt(" #n ")" ::: "memory")
; #define PG8_WAIT_L(n) asm volatile("s_waitcnt lgkmcnt(" #n ")" ::: "memory")
; #define PG8_BAR __builtin_amdgcn_s_barrier()
; #define PG8_SCHED __builtin_amdgcn_sched_barrier(0)
; template <class Epi, class Sched, bool ALIGN_EPI = false, bool SP2 = false>
; __device__ __forceinline__ void gemm_phase(PG8_LAS unsigned char* lds, const Gemm g, const Sched& S, const Epi& E) {
;     ...
;             const char* a1 = cA + (size_t)(t + 1) * kstep;
;             const char* a2 = last ? nA : cA + (size_t)(t + 2) * kstep; const char* b2 = last ? nB : cB + (size_t)(t + 2) * kstep;
;             const char* a3 = a2 + kstep; const char* b3 = b2 + kstep;
;             if (last && has_next) S.a_ready(nxt);
;             if constexpr (SP2) {
;             PG8_LDB(B0, 0, 0); PG8_LDB(B1, 0, 1); PG8_SCHED; PG8_LDA(At, 0, 0); PG8_STAGE(PG8_SA(1, 1), a1 + hstep, voffA);
;             PG8_WAIT_V(8); PG8_WAIT_L(0); PG8_BAR; PG8_MMA(0, 0, At, B0); PG8_MMA(0, 1, At, B1); PG8_BAR; PG8_SCHED;
;             PG8_LDA(At, 0, 1); PG8_STAGE(PG8_SB(0, 0), b2, voffB); PG8_STAGE(PG8_SB(0, 1), b2 + hstep, voffB); PG8_STAGE(PG8_SA(0, 0), a2, voffA);
.LBB0_458:
	s_add_i32 s96, s66, 2
	s_add_u32 s92, s10, 0x80
	s_addc_u32 s67, s11, 0
	s_add_i32 s93, 0, 0x10000
	s_cmp_eq_u32 s17, s66
	s_cselect_b32 s67, s71, s67
	s_cselect_b32 s66, s70, s92
	s_cselect_b32 vcc_hi, s95, s91
	s_cselect_b32 vcc_lo, s94, s13
	s_add_i32 s92, 0, 0x14000
	v_add_u32_e32 v84, s93, v229
	v_add_u32_e32 v134, s92, v229
	ds_read_b128 v[48:51], v84
	ds_read_b128 v[60:63], v84 offset:1024
	ds_read_b128 v[72:75], v84 offset:2048
	ds_read_b128 v[84:87], v84 offset:3072
	ds_read_b128 v[96:99], v134
	ds_read_b128 v[108:111], v134 offset:1024
	ds_read_b128 v[120:123], v134 offset:2048
	ds_read_b128 v[134:137], v134 offset:3072
	v_lshl_add_u64 v[208:209], s[10:11], 0, v[202:203]
	s_add_i32 m0, s26, 0xc000
	ds_read_b128 v[146:149], v231
	ds_read_b128 v[150:153], v231 offset:1024
	ds_read_b128 v[170:173], v231 offset:2048
	ds_read_b128 v[174:177], v231 offset:3072
	ds_read_b128 v[178:181], v231 offset:4096
	ds_read_b128 v[182:185], v231 offset:5120
	ds_read_b128 v[186:189], v231 offset:6144
	ds_read_b128 v[204:207], v231 offset:7168
	global_load_lds_dwordx4 v[208:209], off
	v_lshl_add_u64 v[208:209], s[10:11], 0, v[200:201]
	s_add_i32 m0, s26, 0xe000
	s_nop 0
	global_load_lds_dwordx4 v[208:209], off
	s_waitcnt vmcnt(8)
	s_waitcnt lgkmcnt(0)
	s_barrier
	s_setprio 1
	v_mfma_f32_16x16x32_bf16 v[166:169], v[48:51], v[146:149], v[166:169]
	v_mfma_f32_16x16x32_bf16 v[162:165], v[72:75], v[146:149], v[162:165]
	v_mfma_f32_16x16x32_bf16 v[142:145], v[48:51], v[170:173], v[142:145]
	v_mfma_f32_16x16x32_bf16 v[138:141], v[72:75], v[170:173], v[138:141]
	v_mfma_f32_16x16x32_bf16 v[116:119], v[48:51], v[178:181], v[116:119]
	v_mfma_f32_16x16x32_bf16 v[112:115], v[72:75], v[178:181], v[112:115]
	v_mfma_f32_16x16x32_bf16 v[92:95], v[48:51], v[186:189], v[92:95]
	v_mfma_f32_16x16x32_bf16 v[88:91], v[72:75], v[186:189], v[88:91]
	v_mfma_f32_16x16x32_bf16 v[166:169], v[60:63], v[150:153], v[166:169]
	v_mfma_f32_16x16x32_bf16 v[162:165], v[84:87], v[150:153], v[162:165]
	v_mfma_f32_16x16x32_bf16 v[142:145], v[60:63], v[174:177], v[142:145]
	v_mfma_f32_16x16x32_bf16 v[138:141], v[84:87], v[174:177], v[138:141]
	v_mfma_f32_16x16x32_bf16 v[116:119], v[60:63], v[182:185], v[116:119]
	v_mfma_f32_16x16x32_bf16 v[112:115], v[84:87], v[182:185], v[112:115]
	v_mfma_f32_16x16x32_bf16 v[92:95], v[60:63], v[204:207], v[92:95]
	v_mfma_f32_16x16x32_bf16 v[88:91], v[84:87], v[204:207], v[88:91]
	v_mfma_f32_16x16x32_bf16 v[158:161], v[96:99], v[146:149], v[158:161]
	v_mfma_f32_16x16x32_bf16 v[130:133], v[96:99], v[170:173], v[130:133]
	v_mfma_f32_16x16x32_bf16 v[124:127], v[120:123], v[170:173], v[124:127]
	v_mfma_f32_16x16x32_bf16 v[104:107], v[96:99], v[178:181], v[104:107]
	v_mfma_f32_16x16x32_bf16 v[100:103], v[120:123], v[178:181], v[100:103]
	v_mfma_f32_16x16x32_bf16 v[80:83], v[96:99], v[186:189], v[80:83]
	v_mfma_f32_16x16x32_bf16 v[76:79], v[120:123], v[186:189], v[76:79]
	v_mfma_f32_16x16x32_bf16 v[158:161], v[108:111], v[150:153], v[158:161]
	v_mfma_f32_16x16x32_bf16 v[146:149], v[120:123], v[146:149], v[154:157]
	v_mfma_f32_16x16x32_bf16 v[130:133], v[108:111], v[174:177], v[130:133]
	v_mfma_f32_16x16x32_bf16 v[124:127], v[134:137], v[174:177], v[124:127]
	v_mfma_f32_16x16x32_bf16 v[104:107], v[108:111], v[182:185], v[104:107]
	v_mfma_f32_16x16x32_bf16 v[100:103], v[134:137], v[182:185], v[100:103]
	v_mfma_f32_16x16x32_bf16 v[80:83], v[108:111], v[204:207], v[80:83]
	v_mfma_f32_16x16x32_bf16 v[76:79], v[134:137], v[204:207], v[76:79]
	v_mfma_f32_16x16x32_bf16 v[146:149], v[134:137], v[150:153], v[146:149]
	s_setprio 0
	s_barrier
	s_add_i32 s93, s93, s20
	v_lshl_add_u64 v[208:209], vcc, 0, v[128:129]
	s_mov_b32 m0, s93
	ds_read_b128 v[150:153], v231 offset:16384
	ds_read_b128 v[154:157], v231 offset:17408
	ds_read_b128 v[170:173], v231 offset:18432
	ds_read_b128 v[174:177], v231 offset:19456
	ds_read_b128 v[178:181], v231 offset:20480
	ds_read_b128 v[182:185], v231 offset:21504
	ds_read_b128 v[186:189], v231 offset:22528
	ds_read_b128 v[204:207], v231 offset:23552
	global_load_lds_dwordx4 v[208:209], off
	s_add_i32 m0, s93, 0x2000
	v_lshl_add_u64 v[210:211], vcc, 0, v[194:195]
	s_add_u32 vcc_lo, vcc_lo, s0
	s_addc_u32 vcc_hi, vcc_hi, 0
	s_add_i32 s92, s92, s20
	global_load_lds_dwordx4 v[210:211], off
	v_lshl_add_u64 v[212:213], vcc, 0, v[128:129]
	s_mov_b32 m0, s92
	v_lshl_add_u64 v[214:215], vcc, 0, v[194:195]
	global_load_lds_dwordx4 v[212:213], off
	s_add_i32 m0, s92, 0x2000
	v_lshl_add_u64 v[216:217], s[66:67], 0, v[190:191]
	global_load_lds_dwordx4 v[214:215], off
	s_mov_b32 m0, s26
	v_lshl_add_u64 v[218:219], s[66:67], 0, v[192:193]
	global_load_lds_dwordx4 v[216:217], off
	s_mov_b32 m0, s27
	s_nop 0
	global_load_lds_dwordx4 v[218:219], off
	s_waitcnt vmcnt(8)
	s_waitcnt lgkmcnt(0)
	s_barrier
; #define PG8_STAGE(bufoff, gbase, voff) do { _Pragma("unroll") for (int _i = 0; _i < 2; ++_i) \
;         __builtin_amdgcn_global_load_lds((const unsigned*)((const char*)(gbase) + (voff)[_i]), (PG8_LAS unsigned*)(lds + (bufoff) + ldsw + _i * 8192), 16, 0, 0); } while (0)
; #define PG8_LDA(dst, b, h) do { _Pragma("unroll") for (int m = 0; m < 4; ++m) _Pragma("unroll") for (int k = 0; k < 2; ++k) dst[m][k] = *(const PG8_LAS bf16x8*)(lds + PG8_SA(b, h) + aoff + m * 2048 + k * 1024); } while (0)
; #define PG8_LDB(dst, b, h) do { _Pragma("unroll") for (int n = 0; n < 2; ++n) _Pragma("unroll") for (int k = 0; k < 2; ++k) dst[n][k] = *(const PG8_LAS bf16x8*)(lds + PG8_SB(b, h) + boff + n * 2048 + k * 1024); } while (0)
; #define PG8_MMA(ai, bj, At, Bt) do { __builtin_amdgcn_s_setprio(1); _Pragma("unroll") for (int m = 0; m < 4; ++m) _Pragma("unroll") for (int n = 0; n < 2; ++n) _Pragma("unroll") for (int k = 0; k < 2; ++k) \
;         acc[ai][bj][m][n] = __builtin_amdgcn_mfma_f32_16x16x32_bf16(Bt[n][k], At[m][k], acc[ai][bj][m][n], 0, 0, 0); __builtin_amdgcn_s_setprio(0); } while (0)
; #define PG8_WAIT_V(n) asm volatile("s_waitcnt vmcnt(" #n ")" ::: "memory")
; #define PG8_WAIT_L(n) asm volatile("s_waitcnt lgkmcnt(" #n ")" ::: "memory")
; #define PG8_BAR __builtin_amdgcn_s_barrier()
; #define PG8_SCHED __builtin_amdgcn_sched_barrier(0)
; template <class Epi, class Sched, bool ALIGN_EPI = false, bool SP2 = false>
; __device__ __forceinline__ void gemm_phase(PG8_LAS unsigned char* lds, const Gemm g, const Sched& S, const Epi& E) {
;     ...
;             PG8_LDA(At, 0, 1); PG8_STAGE(PG8_SB(0, 0), b2, voffB); PG8_STAGE(PG8_SB(0, 1), b2 + hstep, voffB); PG8_STAGE(PG8_SA(0, 0), a2, voffA);
;             PG8_WAIT_V(8); PG8_WAIT_L(0); PG8_BAR; PG8_MMA(1, 0, At, B0); PG8_MMA(1, 1, At, B1); PG8_BAR; PG8_SCHED;
;             PG8_LDB(B0, 1, 0); PG8_LDB(B1, 1, 1); PG8_SCHED; PG8_LDA(At, 1, 0); PG8_STAGE(PG8_SA(0, 1), a2 + hstep, voffA);
;             PG8_WAIT_V(8); PG8_WAIT_L(0); PG8_BAR; PG8_MMA(0, 0, At, B0); PG8_MMA(0, 1, At, B1); PG8_BAR; PG8_SCHED;
;             PG8_LDA(At, 1, 1); PG8_STAGE(PG8_SB(1, 0), b3, voffB); PG8_STAGE(PG8_SB(1, 1), b3 + hstep, voffB); PG8_STAGE(PG8_SA(1, 0), a3, voffA);
	s_setprio 1
	v_mfma_f32_16x16x32_bf16 v[68:71], v[48:51], v[150:153], v[68:71]
	v_mfma_f32_16x16x32_bf16 v[64:67], v[72:75], v[150:153], v[64:67]
	v_mfma_f32_16x16x32_bf16 v[44:47], v[48:51], v[170:173], v[44:47]
	v_mfma_f32_16x16x32_bf16 v[40:43], v[72:75], v[170:173], v[40:43]
	v_mfma_f32_16x16x32_bf16 v[28:31], v[48:51], v[178:181], v[28:31]
	v_mfma_f32_16x16x32_bf16 v[24:27], v[72:75], v[178:181], v[24:27]
	v_mfma_f32_16x16x32_bf16 v[12:15], v[48:51], v[186:189], v[12:15]
	v_mfma_f32_16x16x32_bf16 v[8:11], v[72:75], v[186:189], v[8:11]
	v_mfma_f32_16x16x32_bf16 v[68:71], v[60:63], v[154:157], v[68:71]
	v_mfma_f32_16x16x32_bf16 v[64:67], v[84:87], v[154:157], v[64:67]
	v_mfma_f32_16x16x32_bf16 v[44:47], v[60:63], v[174:177], v[44:47]
	v_mfma_f32_16x16x32_bf16 v[40:43], v[84:87], v[174:177], v[40:43]
	v_mfma_f32_16x16x32_bf16 v[28:31], v[60:63], v[182:185], v[28:31]
	v_mfma_f32_16x16x32_bf16 v[24:27], v[84:87], v[182:185], v[24:27]
	v_mfma_f32_16x16x32_bf16 v[12:15], v[60:63], v[204:207], v[12:15]
	v_mfma_f32_16x16x32_bf16 v[8:11], v[84:87], v[204:207], v[8:11]
	v_mfma_f32_16x16x32_bf16 v[52:55], v[120:123], v[150:153], v[52:55]
	v_mfma_f32_16x16x32_bf16 v[36:39], v[96:99], v[170:173], v[36:39]
	v_mfma_f32_16x16x32_bf16 v[32:35], v[120:123], v[170:173], v[32:35]
	v_mfma_f32_16x16x32_bf16 v[20:23], v[96:99], v[178:181], v[20:23]
	v_mfma_f32_16x16x32_bf16 v[16:19], v[120:123], v[178:181], v[16:19]
	v_mfma_f32_16x16x32_bf16 v[4:7], v[96:99], v[186:189], v[4:7]
	v_mfma_f32_16x16x32_bf16 v[0:3], v[120:123], v[186:189], v[0:3]
	v_mfma_f32_16x16x32_bf16 v[48:51], v[96:99], v[150:153], v[56:59]
	v_mfma_f32_16x16x32_bf16 v[52:55], v[134:137], v[154:157], v[52:55]
	v_mfma_f32_16x16x32_bf16 v[36:39], v[108:111], v[174:177], v[36:39]
	v_mfma_f32_16x16x32_bf16 v[32:35], v[134:137], v[174:177], v[32:35]
	v_mfma_f32_16x16x32_bf16 v[20:23], v[108:111], v[182:185], v[20:23]
	v_mfma_f32_16x16x32_bf16 v[16:19], v[134:137], v[182:185], v[16:19]
	v_mfma_f32_16x16x32_bf16 v[4:7], v[108:111], v[204:207], v[4:7]
	v_mfma_f32_16x16x32_bf16 v[0:3], v[134:137], v[204:207], v[0:3]
	v_mfma_f32_16x16x32_bf16 v[48:51], v[108:111], v[154:157], v[48:51]
	s_setprio 0
	s_barrier
	s_add_i32 s92, 0, 0x18000
	s_add_i32 s93, 0, 0x1c000
	v_add_u32_e32 v84, s92, v229
	v_add_u32_e32 v134, s93, v229
	ds_read_b128 v[56:59], v84
	ds_read_b128 v[60:63], v84 offset:1024
	ds_read_b128 v[72:75], v84 offset:2048
	ds_read_b128 v[84:87], v84 offset:3072
	ds_read_b128 v[96:99], v134
	ds_read_b128 v[108:111], v134 offset:1024
	ds_read_b128 v[120:123], v134 offset:2048
	ds_read_b128 v[134:137], v134 offset:3072
	s_add_u32 s66, s66, s0
	s_addc_u32 s67, s67, 0
	s_mov_b32 m0, s18
	v_lshl_add_u64 v[220:221], s[66:67], 0, v[190:191]
	ds_read_b128 v[150:153], v231 offset:32768
	ds_read_b128 v[154:157], v231 offset:33792
	ds_read_b128 v[170:173], v231 offset:34816
	ds_read_b128 v[174:177], v231 offset:35840
	ds_read_b128 v[178:181], v231 offset:36864
	ds_read_b128 v[182:185], v231 offset:37888
	ds_read_b128 v[186:189], v231 offset:38912
	ds_read_b128 v[204:207], v231 offset:39936
	global_load_lds_dwordx4 v[220:221], off
	v_lshl_add_u64 v[220:221], s[66:67], 0, v[192:193]
	s_mov_b32 m0, s19
	s_nop 0
	global_load_lds_dwordx4 v[220:221], off
	s_waitcnt vmcnt(8)
	s_waitcnt lgkmcnt(0)
	s_barrier
	s_setprio 1
	v_mfma_f32_16x16x32_bf16 v[166:169], v[56:59], v[150:153], v[166:169]
	v_mfma_f32_16x16x32_bf16 v[162:165], v[72:75], v[150:153], v[162:165]
	v_mfma_f32_16x16x32_bf16 v[142:145], v[56:59], v[170:173], v[142:145]
	v_mfma_f32_16x16x32_bf16 v[138:141], v[72:75], v[170:173], v[138:141]
	v_mfma_f32_16x16x32_bf16 v[116:119], v[56:59], v[178:181], v[116:119]
	v_mfma_f32_16x16x32_bf16 v[112:115], v[72:75], v[178:181], v[112:115]
	v_mfma_f32_16x16x32_bf16 v[92:95], v[56:59], v[186:189], v[92:95]
	v_mfma_f32_16x16x32_bf16 v[88:91], v[72:75], v[186:189], v[88:91]
	v_mfma_f32_16x16x32_bf16 v[166:169], v[60:63], v[154:157], v[166:169]
	v_mfma_f32_16x16x32_bf16 v[162:165], v[84:87], v[154:157], v[162:165]
	v_mfma_f32_16x16x32_bf16 v[142:145], v[60:63], v[174:177], v[142:145]
	v_mfma_f32_16x16x32_bf16 v[138:141], v[84:87], v[174:177], v[138:141]
	v_mfma_f32_16x16x32_bf16 v[116:119], v[60:63], v[182:185], v[116:119]
	v_mfma_f32_16x16x32_bf16 v[112:115], v[84:87], v[182:185], v[112:115]
	v_mfma_f32_16x16x32_bf16 v[92:95], v[60:63], v[204:207], v[92:95]
	v_mfma_f32_16x16x32_bf16 v[88:91], v[84:87], v[204:207], v[88:91]
	v_mfma_f32_16x16x32_bf16 v[158:161], v[96:99], v[150:153], v[158:161]
	v_mfma_f32_16x16x32_bf16 v[146:149], v[120:123], v[150:153], v[146:149]
	v_mfma_f32_16x16x32_bf16 v[130:133], v[96:99], v[170:173], v[130:133]
	v_mfma_f32_16x16x32_bf16 v[124:127], v[120:123], v[170:173], v[124:127]
	v_mfma_f32_16x16x32_bf16 v[104:107], v[96:99], v[178:181], v[104:107]
	v_mfma_f32_16x16x32_bf16 v[100:103], v[120:123], v[178:181], v[100:103]
	v_mfma_f32_16x16x32_bf16 v[80:83], v[96:99], v[186:189], v[80:83]
	v_mfma_f32_16x16x32_bf16 v[76:79], v[120:123], v[186:189], v[76:79]
	v_mfma_f32_16x16x32_bf16 v[158:161], v[108:111], v[154:157], v[158:161]
	v_mfma_f32_16x16x32_bf16 v[154:157], v[134:137], v[154:157], v[146:149]
	v_mfma_f32_16x16x32_bf16 v[130:133], v[108:111], v[174:177], v[130:133]
	v_mfma_f32_16x16x32_bf16 v[124:127], v[134:137], v[174:177], v[124:127]
	v_mfma_f32_16x16x32_bf16 v[104:107], v[108:111], v[182:185], v[104:107]
	v_mfma_f32_16x16x32_bf16 v[100:103], v[134:137], v[182:185], v[100:103]
	v_mfma_f32_16x16x32_bf16 v[80:83], v[108:111], v[204:207], v[80:83]
	v_mfma_f32_16x16x32_bf16 v[76:79], v[134:137], v[204:207], v[76:79]
	s_setprio 0
	s_barrier
; #define PG8_STAGE(bufoff, gbase, voff) do { _Pragma("unroll") for (int _i = 0; _i < 2; ++_i) \
;         __builtin_amdgcn_global_load_lds((const unsigned*)((const char*)(gbase) + (voff)[_i]), (PG8_LAS unsigned*)(lds + (bufoff) + ldsw + _i * 8192), 16, 0, 0); } while (0)
; #define PG8_LDA(dst, b, h) do { _Pragma("unroll") for (int m = 0; m < 4; ++m) _Pragma("unroll") for (int k = 0; k < 2; ++k) dst[m][k] = *(const PG8_LAS bf16x8*)(lds + PG8_SA(b, h) + aoff + m * 2048 + k * 1024); } while (0)
; #define PG8_MMA(ai, bj, At, Bt) do { __builtin_amdgcn_s_setprio(1); _Pragma("unroll") for (int m = 0; m < 4; ++m) _Pragma("unroll") for (int n = 0; n < 2; ++n) _Pragma("unroll") for (int k = 0; k < 2; ++k) \
;         acc[ai][bj][m][n] = __builtin_amdgcn_mfma_f32_16x16x32_bf16(Bt[n][k], At[m][k], acc[ai][bj][m][n], 0, 0, 0); __builtin_amdgcn_s_setprio(0); } while (0)
; #define PG8_WAIT_V(n) asm volatile("s_waitcnt vmcnt(" #n ")" ::: "memory")
; #define PG8_WAIT_L(n) asm volatile("s_waitcnt lgkmcnt(" #n ")" ::: "memory")
; #define PG8_BAR __builtin_amdgcn_s_barrier()
; #define PG8_SCHED __builtin_amdgcn_sched_barrier(0)
; template <class Epi, class Sched, bool ALIGN_EPI = false, bool SP2 = false>
; __device__ __forceinline__ void gemm_phase(PG8_LAS unsigned char* lds, const Gemm g, const Sched& S, const Epi& E) {
;     ...
;             PG8_LDA(At, 1, 1); PG8_STAGE(PG8_SB(1, 0), b3, voffB); PG8_STAGE(PG8_SB(1, 1), b3 + hstep, voffB); PG8_STAGE(PG8_SA(1, 0), a3, voffA);
;             PG8_WAIT_V(8); PG8_WAIT_L(0); PG8_BAR; PG8_MMA(1, 0, At, B0); PG8_MMA(1, 1, At, B1); PG8_BAR; PG8_SCHED;
;     ...
;         if constexpr (ALIGN_EPI) { if (wr == 0) PG8_BAR; }
	s_add_i32 s66, s92, s20
	v_lshl_add_u64 v[208:209], v[208:209], 0, s[76:77]
	s_mov_b32 m0, s66
	ds_read_b128 v[146:149], v231 offset:49152
	ds_read_b128 v[150:153], v231 offset:50176
	ds_read_b128 v[170:173], v231 offset:51200
	ds_read_b128 v[174:177], v231 offset:52224
	ds_read_b128 v[178:181], v231 offset:53248
	ds_read_b128 v[182:185], v231 offset:54272
	ds_read_b128 v[186:189], v231 offset:55296
	ds_read_b128 v[204:207], v231 offset:56320
	global_load_lds_dwordx4 v[208:209], off
	v_lshl_add_u64 v[208:209], v[210:211], 0, s[76:77]
	s_add_i32 m0, s66, 0x2000
	s_add_i32 s66, s93, s20
	global_load_lds_dwordx4 v[208:209], off
	v_lshl_add_u64 v[208:209], v[212:213], 0, s[76:77]
	s_mov_b32 m0, s66
	s_nop 0
	global_load_lds_dwordx4 v[208:209], off
	v_lshl_add_u64 v[208:209], v[214:215], 0, s[76:77]
	s_add_i32 m0, s66, 0x2000
	s_nop 0
	global_load_lds_dwordx4 v[208:209], off
	v_lshl_add_u64 v[208:209], v[216:217], 0, s[76:77]
	s_mov_b32 m0, s14
	s_nop 0
	global_load_lds_dwordx4 v[208:209], off
	v_lshl_add_u64 v[208:209], v[218:219], 0, s[76:77]
	s_mov_b32 m0, s72
	s_nop 0
	global_load_lds_dwordx4 v[208:209], off
	s_waitcnt vmcnt(8)
	s_waitcnt lgkmcnt(0)
	s_barrier
	s_setprio 1
	v_mfma_f32_16x16x32_bf16 v[68:71], v[56:59], v[146:149], v[68:71]
	v_mfma_f32_16x16x32_bf16 v[64:67], v[72:75], v[146:149], v[64:67]
	v_mfma_f32_16x16x32_bf16 v[44:47], v[56:59], v[170:173], v[44:47]
	v_mfma_f32_16x16x32_bf16 v[40:43], v[72:75], v[170:173], v[40:43]
	v_mfma_f32_16x16x32_bf16 v[28:31], v[56:59], v[178:181], v[28:31]
	v_mfma_f32_16x16x32_bf16 v[24:27], v[72:75], v[178:181], v[24:27]
	v_mfma_f32_16x16x32_bf16 v[12:15], v[56:59], v[186:189], v[12:15]
	v_mfma_f32_16x16x32_bf16 v[8:11], v[72:75], v[186:189], v[8:11]
	v_mfma_f32_16x16x32_bf16 v[68:71], v[60:63], v[150:153], v[68:71]
	v_mfma_f32_16x16x32_bf16 v[64:67], v[84:87], v[150:153], v[64:67]
	v_mfma_f32_16x16x32_bf16 v[44:47], v[60:63], v[174:177], v[44:47]
	v_mfma_f32_16x16x32_bf16 v[40:43], v[84:87], v[174:177], v[40:43]
	v_mfma_f32_16x16x32_bf16 v[28:31], v[60:63], v[182:185], v[28:31]
	v_mfma_f32_16x16x32_bf16 v[24:27], v[84:87], v[182:185], v[24:27]
	v_mfma_f32_16x16x32_bf16 v[12:15], v[60:63], v[204:207], v[12:15]
	v_mfma_f32_16x16x32_bf16 v[8:11], v[84:87], v[204:207], v[8:11]
	v_mfma_f32_16x16x32_bf16 v[48:51], v[96:99], v[146:149], v[48:51]
	v_mfma_f32_16x16x32_bf16 v[56:59], v[108:111], v[150:153], v[48:51]
	v_mfma_f32_16x16x32_bf16 v[48:51], v[120:123], v[146:149], v[52:55]
	v_mfma_f32_16x16x32_bf16 v[36:39], v[96:99], v[170:173], v[36:39]
	v_mfma_f32_16x16x32_bf16 v[32:35], v[120:123], v[170:173], v[32:35]
	v_mfma_f32_16x16x32_bf16 v[20:23], v[96:99], v[178:181], v[20:23]
	v_mfma_f32_16x16x32_bf16 v[16:19], v[120:123], v[178:181], v[16:19]
	v_mfma_f32_16x16x32_bf16 v[4:7], v[96:99], v[186:189], v[4:7]
	v_mfma_f32_16x16x32_bf16 v[0:3], v[120:123], v[186:189], v[0:3]
	v_mfma_f32_16x16x32_bf16 v[52:55], v[134:137], v[150:153], v[48:51]
	v_mfma_f32_16x16x32_bf16 v[36:39], v[108:111], v[174:177], v[36:39]
	v_mfma_f32_16x16x32_bf16 v[32:35], v[134:137], v[174:177], v[32:35]
	v_mfma_f32_16x16x32_bf16 v[20:23], v[108:111], v[182:185], v[20:23]
	v_mfma_f32_16x16x32_bf16 v[16:19], v[134:137], v[182:185], v[16:19]
	v_mfma_f32_16x16x32_bf16 v[4:7], v[108:111], v[204:207], v[4:7]
	v_mfma_f32_16x16x32_bf16 v[0:3], v[134:137], v[204:207], v[0:3]
	s_setprio 0
	s_barrier
	s_add_u32 s13, s13, 0x100
	s_addc_u32 s91, s91, 0
	s_add_u32 s10, s10, 0x100
	s_addc_u32 s11, s11, 0
	s_cmp_ge_u32 s96, s16
	s_mov_b32 s66, s96
	s_cbranch_scc0 .LBB0_458
	s_and_b64 vcc, exec, s[60:61]
	s_cbranch_vccz .LBB0_461
	s_barrier

; #define PG8_STAGE(bufoff, gbase, voff) do { _Pragma("unroll") for (int _i = 0; _i < 2; ++_i) \
;         __builtin_amdgcn_global_load_lds((const unsigned*)((const char*)(gbase) + (voff)[_i]), (PG8_LAS unsigned*)(lds + (bufoff) + ldsw + _i * 8192), 16, 0, 0); } while (0)
; #define PG8_LDA(dst, b, h) do { _Pragma("unroll") for (int m = 0; m < 4; ++m) _Pragma("unroll") for (int k = 0; k < 2; ++k) dst[m][k] = *(const PG8_LAS bf16x8*)(lds + PG8_SA(b, h) + aoff + m * 2048 + k * 1024); } while (0)
; #define PG8_LDB(dst, b, h) do { _Pragma("unroll") for (int n = 0; n < 2; ++n) _Pragma("unroll") for (int k = 0; k < 2; ++k) dst[n][k] = *(const PG8_LAS bf16x8*)(lds + PG8_SB(b, h) + boff + n * 2048 + k * 1024); } while (0)
; #define PG8_MMA(ai, bj, At, Bt) do { __builtin_amdgcn_s_setprio(1); _Pragma("unroll") for (int m = 0; m < 4; ++m) _Pragma("unroll") for (int n = 0; n < 2; ++n) _Pragma("unroll") for (int k = 0; k < 2; ++k) \
;         acc[ai][bj][m][n] = __builtin_amdgcn_mfma_f32_16x16x32_bf16(Bt[n][k], At[m][k], acc[ai][bj][m][n], 0, 0, 0); __builtin_amdgcn_s_setprio(0); } while (0)
; #define PG8_WAIT_V(n) asm volatile("s_waitcnt vmcnt(" #n ")" ::: "memory")
; #define PG8_WAIT_L(n) asm volatile("s_waitcnt lgkmcnt(" #n ")" ::: "memory")
; #define PG8_BAR __builtin_amdgcn_s_barrier()
; #define PG8_SCHED __builtin_amdgcn_sched_barrier(0)
; template <class Epi, class Sched, bool ALIGN_EPI = false, bool SP2 = false>
; __device__ __forceinline__ void gemm_phase(PG8_LAS unsigned char* lds, const Gemm g, const Sched& S, const Epi& E) {
;     ...
;             const char* a1 = cA + (size_t)(t + 1) * kstep;
;             const char* a2 = last ? nA : cA + (size_t)(t + 2) * kstep; const char* b2 = last ? nB : cB + (size_t)(t + 2) * kstep;
;             const char* a3 = a2 + kstep; const char* b3 = b2 + kstep;
;             if (last && has_next) S.a_ready(nxt);
;             if constexpr (SP2) {
;             PG8_LDB(B0, 0, 0); PG8_LDB(B1, 0, 1); PG8_SCHED; PG8_LDA(At, 0, 0); PG8_STAGE(PG8_SA(1, 1), a1 + hstep, voffA);
;             PG8_WAIT_V(8); PG8_WAIT_L(0); PG8_BAR; PG8_MMA(0, 0, At, B0); PG8_MMA(0, 1, At, B1); PG8_BAR; PG8_SCHED;
;             PG8_LDA(At, 0, 1); PG8_STAGE(PG8_SB(0, 0), b2, voffB); PG8_STAGE(PG8_SB(0, 1), b2 + hstep, voffB); PG8_STAGE(PG8_SA(0, 0), a2, voffA);
.LBB0_590:
	s_add_u32 s8, s0, 0xfff80080
	s_addc_u32 s9, s1, -1
	s_add_i32 s61, 0, 0x10000
	s_cmp_eq_u32 s60, 28
	s_cselect_b32 s29, s14, s9
	s_cselect_b32 s28, s26, s8
	v_add_u32_e32 v128, s61, v187
	s_cselect_b32 s9, s27, s35
	s_cselect_b32 s8, s31, s34
	s_add_i32 s65, 0, 0x14000
	ds_read_b128 v[56:59], v128
	ds_read_b128 v[138:141], v128 offset:1024
	ds_read_b128 v[142:145], v128 offset:2048
	ds_read_b128 v[160:163], v128 offset:3072
	v_add_u32_e32 v128, s65, v187
	ds_read_b128 v[164:167], v128
	ds_read_b128 v[176:179], v128 offset:1024
	ds_read_b128 v[180:183], v128 offset:2048
	ds_read_b128 v[190:193], v128 offset:3072
	v_lshl_add_u64 v[168:169], s[0:1], 0, v[158:159]
	s_add_i32 m0, s5, 0xc000
	ds_read_b128 v[194:197], v189
	ds_read_b128 v[198:201], v189 offset:1024
	ds_read_b128 v[202:205], v189 offset:2048
	ds_read_b128 v[206:209], v189 offset:3072
	ds_read_b128 v[210:213], v189 offset:4096
	ds_read_b128 v[214:217], v189 offset:5120
	ds_read_b128 v[218:221], v189 offset:6144
	ds_read_b128 v[222:225], v189 offset:7168
	global_load_lds_dwordx4 v[168:169], off
	v_lshl_add_u64 v[168:169], s[0:1], 0, v[156:157]
	s_add_i32 m0, s5, 0xe000
	s_nop 0
	global_load_lds_dwordx4 v[168:169], off
	s_waitcnt vmcnt(8)
	s_waitcnt lgkmcnt(0)
	s_barrier
	s_setprio 1
	v_mfma_f32_16x16x32_bf16 v[134:137], v[56:59], v[194:197], v[134:137]
	v_mfma_f32_16x16x32_bf16 v[124:127], v[142:145], v[194:197], v[124:127]
	v_mfma_f32_16x16x32_bf16 v[116:119], v[56:59], v[202:205], v[116:119]
	v_mfma_f32_16x16x32_bf16 v[104:107], v[142:145], v[202:205], v[104:107]
	v_mfma_f32_16x16x32_bf16 v[96:99], v[56:59], v[210:213], v[96:99]
	v_mfma_f32_16x16x32_bf16 v[88:91], v[142:145], v[210:213], v[88:91]
	v_mfma_f32_16x16x32_bf16 v[80:83], v[56:59], v[218:221], v[80:83]
	v_mfma_f32_16x16x32_bf16 v[72:75], v[142:145], v[218:221], v[72:75]
	v_mfma_f32_16x16x32_bf16 v[134:137], v[138:141], v[198:201], v[134:137]
	v_mfma_f32_16x16x32_bf16 v[124:127], v[160:163], v[198:201], v[124:127]
	v_mfma_f32_16x16x32_bf16 v[116:119], v[138:141], v[206:209], v[116:119]
	v_mfma_f32_16x16x32_bf16 v[104:107], v[160:163], v[206:209], v[104:107]
	v_mfma_f32_16x16x32_bf16 v[96:99], v[138:141], v[214:217], v[96:99]
	v_mfma_f32_16x16x32_bf16 v[88:91], v[160:163], v[214:217], v[88:91]
	v_mfma_f32_16x16x32_bf16 v[80:83], v[138:141], v[222:225], v[80:83]
	v_mfma_f32_16x16x32_bf16 v[72:75], v[160:163], v[222:225], v[72:75]
	v_mfma_f32_16x16x32_bf16 v[130:133], v[164:167], v[194:197], v[130:133]
	v_mfma_f32_16x16x32_bf16 v[120:123], v[180:183], v[194:197], v[120:123]
	v_mfma_f32_16x16x32_bf16 v[112:115], v[164:167], v[202:205], v[112:115]
	v_mfma_f32_16x16x32_bf16 v[100:103], v[180:183], v[202:205], v[100:103]
	v_mfma_f32_16x16x32_bf16 v[92:95], v[164:167], v[210:213], v[92:95]
	v_mfma_f32_16x16x32_bf16 v[84:87], v[180:183], v[210:213], v[84:87]
	v_mfma_f32_16x16x32_bf16 v[76:79], v[164:167], v[218:221], v[76:79]
	v_mfma_f32_16x16x32_bf16 v[68:71], v[180:183], v[218:221], v[68:71]
	v_mfma_f32_16x16x32_bf16 v[130:133], v[176:179], v[198:201], v[130:133]
	v_mfma_f32_16x16x32_bf16 v[120:123], v[190:193], v[198:201], v[120:123]
	v_mfma_f32_16x16x32_bf16 v[112:115], v[176:179], v[206:209], v[112:115]
	v_mfma_f32_16x16x32_bf16 v[100:103], v[190:193], v[206:209], v[100:103]
	v_mfma_f32_16x16x32_bf16 v[92:95], v[176:179], v[214:217], v[92:95]
	v_mfma_f32_16x16x32_bf16 v[84:87], v[190:193], v[214:217], v[84:87]
	v_mfma_f32_16x16x32_bf16 v[76:79], v[176:179], v[222:225], v[76:79]
	v_mfma_f32_16x16x32_bf16 v[68:71], v[190:193], v[222:225], v[68:71]
	s_setprio 0
	s_barrier
	s_add_i32 s61, s61, s20
	v_lshl_add_u64 v[168:169], s[8:9], 0, v[150:151]
	s_mov_b32 m0, s61
	ds_read_b128 v[194:197], v189 offset:16384
	ds_read_b128 v[198:201], v189 offset:17408
	ds_read_b128 v[202:205], v189 offset:18432
	ds_read_b128 v[206:209], v189 offset:19456
	ds_read_b128 v[210:213], v189 offset:20480
	ds_read_b128 v[214:217], v189 offset:21504
	ds_read_b128 v[218:221], v189 offset:22528
	ds_read_b128 v[222:225], v189 offset:23552
	global_load_lds_dwordx4 v[168:169], off
	s_add_i32 m0, s61, 0x2000
	s_add_u32 s66, s8, 0x80000
	v_lshl_add_u64 v[184:185], s[8:9], 0, v[146:147]
	s_addc_u32 s67, s9, 0
	s_add_i32 s61, s65, s20
	global_load_lds_dwordx4 v[184:185], off
	v_lshl_add_u64 v[226:227], s[66:67], 0, v[150:151]
	s_mov_b32 m0, s61
	v_lshl_add_u64 v[228:229], s[28:29], 0, v[148:149]
	global_load_lds_dwordx4 v[226:227], off
	v_lshl_add_u64 v[226:227], s[66:67], 0, v[146:147]
	s_add_i32 m0, s61, 0x2000
	s_nop 0
	global_load_lds_dwordx4 v[226:227], off
	v_lshl_add_u64 v[226:227], s[28:29], 0, v[152:153]
	s_mov_b32 m0, s5
	s_nop 0
	global_load_lds_dwordx4 v[226:227], off
	s_mov_b32 m0, s15
	s_nop 0
	global_load_lds_dwordx4 v[228:229], off
	s_waitcnt vmcnt(8)
	s_waitcnt lgkmcnt(0)
	s_barrier
; #define PG8_STAGE(bufoff, gbase, voff) do { _Pragma("unroll") for (int _i = 0; _i < 2; ++_i) \
;         __builtin_amdgcn_global_load_lds((const unsigned*)((const char*)(gbase) + (voff)[_i]), (PG8_LAS unsigned*)(lds + (bufoff) + ldsw + _i * 8192), 16, 0, 0); } while (0)
; #define PG8_LDA(dst, b, h) do { _Pragma("unroll") for (int m = 0; m < 4; ++m) _Pragma("unroll") for (int k = 0; k < 2; ++k) dst[m][k] = *(const PG8_LAS bf16x8*)(lds + PG8_SA(b, h) + aoff + m * 2048 + k * 1024); } while (0)
; #define PG8_LDB(dst, b, h) do { _Pragma("unroll") for (int n = 0; n < 2; ++n) _Pragma("unroll") for (int k = 0; k < 2; ++k) dst[n][k] = *(const PG8_LAS bf16x8*)(lds + PG8_SB(b, h) + boff + n * 2048 + k * 1024); } while (0)
; #define PG8_MMA(ai, bj, At, Bt) do { __builtin_amdgcn_s_setprio(1); _Pragma("unroll") for (int m = 0; m < 4; ++m) _Pragma("unroll") for (int n = 0; n < 2; ++n) _Pragma("unroll") for (int k = 0; k < 2; ++k) \
;         acc[ai][bj][m][n] = __builtin_amdgcn_mfma_f32_16x16x32_bf16(Bt[n][k], At[m][k], acc[ai][bj][m][n], 0, 0, 0); __builtin_amdgcn_s_setprio(0); } while (0)
; #define PG8_WAIT_V(n) asm volatile("s_waitcnt vmcnt(" #n ")" ::: "memory")
; #define PG8_WAIT_L(n) asm volatile("s_waitcnt lgkmcnt(" #n ")" ::: "memory")
; #define PG8_BAR __builtin_amdgcn_s_barrier()
; #define PG8_SCHED __builtin_amdgcn_sched_barrier(0)
; template <class Epi, class Sched, bool ALIGN_EPI = false, bool SP2 = false>
; __device__ __forceinline__ void gemm_phase(PG8_LAS unsigned char* lds, const Gemm g, const Sched& S, const Epi& E) {
;     ...
;             PG8_LDA(At, 0, 1); PG8_STAGE(PG8_SB(0, 0), b2, voffB); PG8_STAGE(PG8_SB(0, 1), b2 + hstep, voffB); PG8_STAGE(PG8_SA(0, 0), a2, voffA);
;             PG8_WAIT_V(8); PG8_WAIT_L(0); PG8_BAR; PG8_MMA(1, 0, At, B0); PG8_MMA(1, 1, At, B1); PG8_BAR; PG8_SCHED;
;             PG8_LDB(B0, 1, 0); PG8_LDB(B1, 1, 1); PG8_SCHED; PG8_LDA(At, 1, 0); PG8_STAGE(PG8_SA(0, 1), a2 + hstep, voffA);
;             PG8_WAIT_V(8); PG8_WAIT_L(0); PG8_BAR; PG8_MMA(0, 0, At, B0); PG8_MMA(0, 1, At, B1); PG8_BAR; PG8_SCHED;
;             PG8_LDA(At, 1, 1); PG8_STAGE(PG8_SB(1, 0), b3, voffB); PG8_STAGE(PG8_SB(1, 1), b3 + hstep, voffB); PG8_STAGE(PG8_SA(1, 0), a3, voffA);
	s_setprio 1
	v_mfma_f32_16x16x32_bf16 v[64:67], v[56:59], v[194:197], v[64:67]
	v_mfma_f32_16x16x32_bf16 v[52:55], v[142:145], v[194:197], v[52:55]
	v_mfma_f32_16x16x32_bf16 v[44:47], v[56:59], v[202:205], v[44:47]
	v_mfma_f32_16x16x32_bf16 v[36:39], v[142:145], v[202:205], v[36:39]
	v_mfma_f32_16x16x32_bf16 v[28:31], v[56:59], v[210:213], v[28:31]
	v_mfma_f32_16x16x32_bf16 v[20:23], v[142:145], v[210:213], v[20:23]
	v_mfma_f32_16x16x32_bf16 v[12:15], v[56:59], v[218:221], v[12:15]
	v_mfma_f32_16x16x32_bf16 v[4:7], v[142:145], v[218:221], v[4:7]
	v_mfma_f32_16x16x32_bf16 v[64:67], v[138:141], v[198:201], v[64:67]
	v_mfma_f32_16x16x32_bf16 v[52:55], v[160:163], v[198:201], v[52:55]
	v_mfma_f32_16x16x32_bf16 v[44:47], v[138:141], v[206:209], v[44:47]
	v_mfma_f32_16x16x32_bf16 v[36:39], v[160:163], v[206:209], v[36:39]
	v_mfma_f32_16x16x32_bf16 v[28:31], v[138:141], v[214:217], v[28:31]
	v_mfma_f32_16x16x32_bf16 v[20:23], v[160:163], v[214:217], v[20:23]
	v_mfma_f32_16x16x32_bf16 v[12:15], v[138:141], v[222:225], v[12:15]
	v_mfma_f32_16x16x32_bf16 v[4:7], v[160:163], v[222:225], v[4:7]
	v_mfma_f32_16x16x32_bf16 v[48:51], v[180:183], v[194:197], v[48:51]
	v_mfma_f32_16x16x32_bf16 v[40:43], v[164:167], v[202:205], v[40:43]
	v_mfma_f32_16x16x32_bf16 v[32:35], v[180:183], v[202:205], v[32:35]
	v_mfma_f32_16x16x32_bf16 v[24:27], v[164:167], v[210:213], v[24:27]
	v_mfma_f32_16x16x32_bf16 v[16:19], v[180:183], v[210:213], v[16:19]
	v_mfma_f32_16x16x32_bf16 v[8:11], v[164:167], v[218:221], v[8:11]
	v_mfma_f32_16x16x32_bf16 v[0:3], v[180:183], v[218:221], v[0:3]
	v_mfma_f32_16x16x32_bf16 v[56:59], v[164:167], v[194:197], v[60:63]
	v_mfma_f32_16x16x32_bf16 v[48:51], v[190:193], v[198:201], v[48:51]
	v_mfma_f32_16x16x32_bf16 v[40:43], v[176:179], v[206:209], v[40:43]
	v_mfma_f32_16x16x32_bf16 v[32:35], v[190:193], v[206:209], v[32:35]
	v_mfma_f32_16x16x32_bf16 v[24:27], v[176:179], v[214:217], v[24:27]
	v_mfma_f32_16x16x32_bf16 v[16:19], v[190:193], v[214:217], v[16:19]
	v_mfma_f32_16x16x32_bf16 v[8:11], v[176:179], v[222:225], v[8:11]
	v_mfma_f32_16x16x32_bf16 v[0:3], v[190:193], v[222:225], v[0:3]
	v_mfma_f32_16x16x32_bf16 v[56:59], v[176:179], v[198:201], v[56:59]
	s_setprio 0
	s_barrier
	s_add_i32 s61, 0, 0x18000
	v_add_u32_e32 v128, s61, v187
	s_add_i32 s65, 0, 0x1c000
	ds_read_b128 v[60:63], v128
	ds_read_b128 v[138:141], v128 offset:1024
	ds_read_b128 v[142:145], v128 offset:2048
	ds_read_b128 v[160:163], v128 offset:3072
	v_add_u32_e32 v128, s65, v187
	ds_read_b128 v[164:167], v128
	ds_read_b128 v[176:179], v128 offset:1024
	ds_read_b128 v[180:183], v128 offset:2048
	ds_read_b128 v[190:193], v128 offset:3072
	s_add_u32 s28, s28, 0x80000
	s_addc_u32 s29, s29, 0
	s_mov_b32 m0, s16
	v_lshl_add_u64 v[230:231], s[28:29], 0, v[152:153]
	ds_read_b128 v[194:197], v189 offset:32768
	ds_read_b128 v[198:201], v189 offset:33792
	ds_read_b128 v[202:205], v189 offset:34816
	ds_read_b128 v[206:209], v189 offset:35840
	ds_read_b128 v[210:213], v189 offset:36864
	ds_read_b128 v[214:217], v189 offset:37888
	ds_read_b128 v[218:221], v189 offset:38912
	ds_read_b128 v[222:225], v189 offset:39936
	global_load_lds_dwordx4 v[230:231], off
	v_lshl_add_u64 v[230:231], s[28:29], 0, v[148:149]
	s_mov_b32 m0, s19
	s_nop 0
	global_load_lds_dwordx4 v[230:231], off
	s_waitcnt vmcnt(8)
	s_waitcnt lgkmcnt(0)
	s_barrier
	s_setprio 1
	v_mfma_f32_16x16x32_bf16 v[134:137], v[60:63], v[194:197], v[134:137]
	v_mfma_f32_16x16x32_bf16 v[124:127], v[142:145], v[194:197], v[124:127]
	v_mfma_f32_16x16x32_bf16 v[116:119], v[60:63], v[202:205], v[116:119]
	v_mfma_f32_16x16x32_bf16 v[104:107], v[142:145], v[202:205], v[104:107]
	v_mfma_f32_16x16x32_bf16 v[96:99], v[60:63], v[210:213], v[96:99]
	v_mfma_f32_16x16x32_bf16 v[88:91], v[142:145], v[210:213], v[88:91]
	v_mfma_f32_16x16x32_bf16 v[80:83], v[60:63], v[218:221], v[80:83]
	v_mfma_f32_16x16x32_bf16 v[72:75], v[142:145], v[218:221], v[72:75]
	v_mfma_f32_16x16x32_bf16 v[134:137], v[138:141], v[198:201], v[134:137]
	v_mfma_f32_16x16x32_bf16 v[124:127], v[160:163], v[198:201], v[124:127]
	v_mfma_f32_16x16x32_bf16 v[116:119], v[138:141], v[206:209], v[116:119]
	v_mfma_f32_16x16x32_bf16 v[104:107], v[160:163], v[206:209], v[104:107]
	v_mfma_f32_16x16x32_bf16 v[96:99], v[138:141], v[214:217], v[96:99]
	v_mfma_f32_16x16x32_bf16 v[88:91], v[160:163], v[214:217], v[88:91]
	v_mfma_f32_16x16x32_bf16 v[80:83], v[138:141], v[222:225], v[80:83]
	v_mfma_f32_16x16x32_bf16 v[72:75], v[160:163], v[222:225], v[72:75]
	v_mfma_f32_16x16x32_bf16 v[130:133], v[164:167], v[194:197], v[130:133]
	v_mfma_f32_16x16x32_bf16 v[120:123], v[180:183], v[194:197], v[120:123]
	v_mfma_f32_16x16x32_bf16 v[112:115], v[164:167], v[202:205], v[112:115]
	v_mfma_f32_16x16x32_bf16 v[100:103], v[180:183], v[202:205], v[100:103]
	v_mfma_f32_16x16x32_bf16 v[92:95], v[164:167], v[210:213], v[92:95]
	v_mfma_f32_16x16x32_bf16 v[84:87], v[180:183], v[210:213], v[84:87]
	v_mfma_f32_16x16x32_bf16 v[76:79], v[164:167], v[218:221], v[76:79]
	v_mfma_f32_16x16x32_bf16 v[68:71], v[180:183], v[218:221], v[68:71]
	v_mfma_f32_16x16x32_bf16 v[130:133], v[176:179], v[198:201], v[130:133]
	v_mfma_f32_16x16x32_bf16 v[120:123], v[190:193], v[198:201], v[120:123]
	v_mfma_f32_16x16x32_bf16 v[112:115], v[176:179], v[206:209], v[112:115]
	v_mfma_f32_16x16x32_bf16 v[100:103], v[190:193], v[206:209], v[100:103]
	v_mfma_f32_16x16x32_bf16 v[92:95], v[176:179], v[214:217], v[92:95]
	v_mfma_f32_16x16x32_bf16 v[84:87], v[190:193], v[214:217], v[84:87]
	v_mfma_f32_16x16x32_bf16 v[76:79], v[176:179], v[222:225], v[76:79]
	v_mfma_f32_16x16x32_bf16 v[68:71], v[190:193], v[222:225], v[68:71]
	s_setprio 0
	s_barrier
; #define PG8_STAGE(bufoff, gbase, voff) do { _Pragma("unroll") for (int _i = 0; _i < 2; ++_i) \
;         __builtin_amdgcn_global_load_lds((const unsigned*)((const char*)(gbase) + (voff)[_i]), (PG8_LAS unsigned*)(lds + (bufoff) + ldsw + _i * 8192), 16, 0, 0); } while (0)
; #define PG8_LDA(dst, b, h) do { _Pragma("unroll") for (int m = 0; m < 4; ++m) _Pragma("unroll") for (int k = 0; k < 2; ++k) dst[m][k] = *(const PG8_LAS bf16x8*)(lds + PG8_SA(b, h) + aoff + m * 2048 + k * 1024); } while (0)
; #define PG8_MMA(ai, bj, At, Bt) do { __builtin_amdgcn_s_setprio(1); _Pragma("unroll") for (int m = 0; m < 4; ++m) _Pragma("unroll") for (int n = 0; n < 2; ++n) _Pragma("unroll") for (int k = 0; k < 2; ++k) \
;         acc[ai][bj][m][n] = __builtin_amdgcn_mfma_f32_16x16x32_bf16(Bt[n][k], At[m][k], acc[ai][bj][m][n], 0, 0, 0); __builtin_amdgcn_s_setprio(0); } while (0)
; #define PG8_WAIT_V(n) asm volatile("s_waitcnt vmcnt(" #n ")" ::: "memory")
; #define PG8_WAIT_L(n) asm volatile("s_waitcnt lgkmcnt(" #n ")" ::: "memory")
; #define PG8_BAR __builtin_amdgcn_s_barrier()
; #define PG8_SCHED __builtin_amdgcn_sched_barrier(0)
; template <class Epi, class Sched, bool ALIGN_EPI = false, bool SP2 = false>
; __device__ __forceinline__ void gemm_phase(PG8_LAS unsigned char* lds, const Gemm g, const Sched& S, const Epi& E) {
;     ...
;             PG8_LDA(At, 1, 1); PG8_STAGE(PG8_SB(1, 0), b3, voffB); PG8_STAGE(PG8_SB(1, 1), b3 + hstep, voffB); PG8_STAGE(PG8_SA(1, 0), a3, voffA);
;             PG8_WAIT_V(8); PG8_WAIT_L(0); PG8_BAR; PG8_MMA(1, 0, At, B0); PG8_MMA(1, 1, At, B1); PG8_BAR; PG8_SCHED;
;     ...
;         if constexpr (ALIGN_EPI) { if (wr == 0) PG8_BAR; }
	s_add_i32 s28, s61, s20
	v_lshl_add_u64 v[168:169], v[168:169], 0, s[76:77]
	s_mov_b32 m0, s28
	ds_read_b128 v[194:197], v189 offset:49152
	ds_read_b128 v[198:201], v189 offset:50176
	ds_read_b128 v[202:205], v189 offset:51200
	ds_read_b128 v[206:209], v189 offset:52224
	ds_read_b128 v[210:213], v189 offset:53248
	ds_read_b128 v[214:217], v189 offset:54272
	ds_read_b128 v[218:221], v189 offset:55296
	ds_read_b128 v[222:225], v189 offset:56320
	global_load_lds_dwordx4 v[168:169], off
	s_add_i32 m0, s28, 0x2000
	s_add_u32 s8, s8, 0x80080
	v_lshl_add_u64 v[168:169], v[184:185], 0, s[76:77]
	s_addc_u32 s9, s9, 0
	s_add_i32 s28, s65, s20
	global_load_lds_dwordx4 v[168:169], off
	v_lshl_add_u64 v[168:169], s[8:9], 0, v[150:151]
	s_mov_b32 m0, s28
	s_nop 0
	global_load_lds_dwordx4 v[168:169], off
	v_lshl_add_u64 v[168:169], s[8:9], 0, v[146:147]
	s_add_i32 m0, s28, 0x2000
	s_nop 0
	global_load_lds_dwordx4 v[168:169], off
	v_lshl_add_u64 v[168:169], v[226:227], 0, s[76:77]
	s_mov_b32 m0, s21
	s_nop 0
	global_load_lds_dwordx4 v[168:169], off
	v_lshl_add_u64 v[168:169], v[228:229], 0, s[76:77]
	s_mov_b32 m0, s22
	s_nop 0
	global_load_lds_dwordx4 v[168:169], off
	s_waitcnt vmcnt(8)
	s_waitcnt lgkmcnt(0)
	s_barrier
	s_setprio 1
	v_mfma_f32_16x16x32_bf16 v[64:67], v[60:63], v[194:197], v[64:67]
	v_mfma_f32_16x16x32_bf16 v[52:55], v[142:145], v[194:197], v[52:55]
	v_mfma_f32_16x16x32_bf16 v[44:47], v[60:63], v[202:205], v[44:47]
	v_mfma_f32_16x16x32_bf16 v[36:39], v[142:145], v[202:205], v[36:39]
	v_mfma_f32_16x16x32_bf16 v[28:31], v[60:63], v[210:213], v[28:31]
	v_mfma_f32_16x16x32_bf16 v[20:23], v[142:145], v[210:213], v[20:23]
	v_mfma_f32_16x16x32_bf16 v[12:15], v[60:63], v[218:221], v[12:15]
	v_mfma_f32_16x16x32_bf16 v[4:7], v[142:145], v[218:221], v[4:7]
	v_mfma_f32_16x16x32_bf16 v[64:67], v[138:141], v[198:201], v[64:67]
	v_mfma_f32_16x16x32_bf16 v[52:55], v[160:163], v[198:201], v[52:55]
	v_mfma_f32_16x16x32_bf16 v[44:47], v[138:141], v[206:209], v[44:47]
	v_mfma_f32_16x16x32_bf16 v[36:39], v[160:163], v[206:209], v[36:39]
	v_mfma_f32_16x16x32_bf16 v[28:31], v[138:141], v[214:217], v[28:31]
	v_mfma_f32_16x16x32_bf16 v[20:23], v[160:163], v[214:217], v[20:23]
	v_mfma_f32_16x16x32_bf16 v[12:15], v[138:141], v[222:225], v[12:15]
	v_mfma_f32_16x16x32_bf16 v[4:7], v[160:163], v[222:225], v[4:7]
	v_mfma_f32_16x16x32_bf16 v[56:59], v[164:167], v[194:197], v[56:59]
	v_mfma_f32_16x16x32_bf16 v[48:51], v[180:183], v[194:197], v[48:51]
	v_mfma_f32_16x16x32_bf16 v[40:43], v[164:167], v[202:205], v[40:43]
	v_mfma_f32_16x16x32_bf16 v[32:35], v[180:183], v[202:205], v[32:35]
	v_mfma_f32_16x16x32_bf16 v[24:27], v[164:167], v[210:213], v[24:27]
	v_mfma_f32_16x16x32_bf16 v[16:19], v[180:183], v[210:213], v[16:19]
	v_mfma_f32_16x16x32_bf16 v[8:11], v[164:167], v[218:221], v[8:11]
	v_mfma_f32_16x16x32_bf16 v[0:3], v[180:183], v[218:221], v[0:3]
	v_mfma_f32_16x16x32_bf16 v[60:63], v[176:179], v[198:201], v[56:59]
	v_mfma_f32_16x16x32_bf16 v[48:51], v[190:193], v[198:201], v[48:51]
	v_mfma_f32_16x16x32_bf16 v[40:43], v[176:179], v[206:209], v[40:43]
	v_mfma_f32_16x16x32_bf16 v[32:35], v[190:193], v[206:209], v[32:35]
	v_mfma_f32_16x16x32_bf16 v[24:27], v[176:179], v[214:217], v[24:27]
	v_mfma_f32_16x16x32_bf16 v[16:19], v[190:193], v[214:217], v[16:19]
	v_mfma_f32_16x16x32_bf16 v[8:11], v[176:179], v[222:225], v[8:11]
	v_mfma_f32_16x16x32_bf16 v[0:3], v[190:193], v[222:225], v[0:3]
	s_setprio 0
	s_barrier
	s_add_i32 s60, s60, 2
	s_add_u32 s34, s34, 0x100
	s_addc_u32 s35, s35, 0
	s_add_u32 s0, s0, 0x100
	s_addc_u32 s1, s1, 0
	s_cmp_gt_u32 s60, 29
	s_cbranch_scc0 .LBB0_590
	s_and_b64 vcc, exec, s[12:13]
	s_cbranch_vccz .LBB0_593
	s_barrier

; #define PG8_STAGE(bufoff, gbase, voff) do { _Pragma("unroll") for (int _i = 0; _i < 2; ++_i) \
;         __builtin_amdgcn_global_load_lds((const unsigned*)((const char*)(gbase) + (voff)[_i]), (PG8_LAS unsigned*)(lds + (bufoff) + ldsw + _i * 8192), 16, 0, 0); } while (0)
; #define PG8_LDA(dst, b, h) do { _Pragma("unroll") for (int m = 0; m < 4; ++m) _Pragma("unroll") for (int k = 0; k < 2; ++k) dst[m][k] = *(const PG8_LAS bf16x8*)(lds + PG8_SA(b, h) + aoff + m * 2048 + k * 1024); } while (0)
; #define PG8_LDB(dst, b, h) do { _Pragma("unroll") for (int n = 0; n < 2; ++n) _Pragma("unroll") for (int k = 0; k < 2; ++k) dst[n][k] = *(const PG8_LAS bf16x8*)(lds + PG8_SB(b, h) + boff + n * 2048 + k * 1024); } while (0)
; #define PG8_MMA(ai, bj, At, Bt) do { __builtin_amdgcn_s_setprio(1); _Pragma("unroll") for (int m = 0; m < 4; ++m) _Pragma("unroll") for (int n = 0; n < 2; ++n) _Pragma("unroll") for (int k = 0; k < 2; ++k) \
;         acc[ai][bj][m][n] = __builtin_amdgcn_mfma_f32_16x16x32_bf16(Bt[n][k], At[m][k], acc[ai][bj][m][n], 0, 0, 0); __builtin_amdgcn_s_setprio(0); } while (0)
; #define PG8_WAIT_V(n) asm volatile("s_waitcnt vmcnt(" #n ")" ::: "memory")
; #define PG8_WAIT_L(n) asm volatile("s_waitcnt lgkmcnt(" #n ")" ::: "memory")
; #define PG8_BAR __builtin_amdgcn_s_barrier()
; #define PG8_SCHED __builtin_amdgcn_sched_barrier(0)
; template <class Epi, class Sched, bool ALIGN_EPI = false, bool SP2 = false>
; __device__ __forceinline__ void gemm_phase(PG8_LAS unsigned char* lds, const Gemm g, const Sched& S, const Epi& E) {
;     ...
;             const char* a1 = cA + (size_t)(t + 1) * kstep;
;             const char* a2 = last ? nA : cA + (size_t)(t + 2) * kstep; const char* b2 = last ? nB : cB + (size_t)(t + 2) * kstep;
;             const char* a3 = a2 + kstep; const char* b3 = b2 + kstep;
;             if (last && has_next) S.a_ready(nxt);
;             if constexpr (SP2) {
;             PG8_LDB(B0, 0, 0); PG8_LDB(B1, 0, 1); PG8_SCHED; PG8_LDA(At, 0, 0); PG8_STAGE(PG8_SA(1, 1), a1 + hstep, voffA);
;             PG8_WAIT_V(8); PG8_WAIT_L(0); PG8_BAR; PG8_MMA(0, 0, At, B0); PG8_MMA(0, 1, At, B1); PG8_BAR; PG8_SCHED;
;             PG8_LDA(At, 0, 1); PG8_STAGE(PG8_SB(0, 0), b2, voffB); PG8_STAGE(PG8_SB(0, 1), b2 + hstep, voffB); PG8_STAGE(PG8_SA(0, 0), a2, voffA);
.LBB0_645:
	s_add_u32 s10, s24, s8
	s_addc_u32 s11, s25, s9
	s_add_u32 s10, s10, 0xc00100
	s_addc_u32 s11, s11, 0
	s_add_u32 s27, s22, s8
	s_addc_u32 s28, s23, s9
	s_add_i32 s29, 0, 0x10000
	s_cmpk_eq_i32 s8, 0xf00
	s_cselect_b32 s13, s7, s11
	s_cselect_b32 s12, s6, s10
	s_cselect_b32 s11, s5, s28
	s_cselect_b32 s10, s4, s27
	s_add_i32 s27, 0, 0x14000
	v_add_u32_e32 v152, s29, v138
	v_add_u32_e32 v168, s27, v138
	ds_read_b128 v[140:143], v152
	ds_read_b128 v[144:147], v152 offset:1024
	ds_read_b128 v[148:151], v152 offset:2048
	ds_read_b128 v[152:155], v152 offset:3072
	ds_read_b128 v[156:159], v168
	ds_read_b128 v[160:163], v168 offset:1024
	ds_read_b128 v[164:167], v168 offset:2048
	ds_read_b128 v[168:171], v168 offset:3072
	v_lshl_add_u64 v[204:205], v[134:135], 0, s[8:9]
	s_add_i32 m0, s15, 0xc000
	ds_read_b128 v[172:175], v139
	ds_read_b128 v[176:179], v139 offset:1024
	ds_read_b128 v[180:183], v139 offset:2048
	ds_read_b128 v[184:187], v139 offset:3072
	ds_read_b128 v[188:191], v139 offset:4096
	ds_read_b128 v[192:195], v139 offset:5120
	ds_read_b128 v[196:199], v139 offset:6144
	ds_read_b128 v[200:203], v139 offset:7168
	global_load_lds_dwordx4 v[204:205], off
	v_lshl_add_u64 v[204:205], v[132:133], 0, s[8:9]
	s_add_i32 m0, s15, 0xe000
	s_nop 0
	global_load_lds_dwordx4 v[204:205], off
	s_waitcnt vmcnt(8)
	s_waitcnt lgkmcnt(0)
	s_barrier
	s_setprio 1
	v_mfma_f32_16x16x32_bf16 v[124:127], v[140:143], v[172:175], v[124:127]
	v_mfma_f32_16x16x32_bf16 v[120:123], v[148:151], v[172:175], v[120:123]
	v_mfma_f32_16x16x32_bf16 v[116:119], v[140:143], v[180:183], v[116:119]
	v_mfma_f32_16x16x32_bf16 v[112:115], v[148:151], v[180:183], v[112:115]
	v_mfma_f32_16x16x32_bf16 v[104:107], v[140:143], v[188:191], v[104:107]
	v_mfma_f32_16x16x32_bf16 v[96:99], v[148:151], v[188:191], v[96:99]
	v_mfma_f32_16x16x32_bf16 v[88:91], v[140:143], v[196:199], v[88:91]
	v_mfma_f32_16x16x32_bf16 v[80:83], v[148:151], v[196:199], v[80:83]
	v_mfma_f32_16x16x32_bf16 v[124:127], v[144:147], v[176:179], v[124:127]
	v_mfma_f32_16x16x32_bf16 v[120:123], v[152:155], v[176:179], v[120:123]
	v_mfma_f32_16x16x32_bf16 v[116:119], v[144:147], v[184:187], v[116:119]
	v_mfma_f32_16x16x32_bf16 v[112:115], v[152:155], v[184:187], v[112:115]
	v_mfma_f32_16x16x32_bf16 v[104:107], v[144:147], v[192:195], v[104:107]
	v_mfma_f32_16x16x32_bf16 v[96:99], v[152:155], v[192:195], v[96:99]
	v_mfma_f32_16x16x32_bf16 v[88:91], v[144:147], v[200:203], v[88:91]
	v_mfma_f32_16x16x32_bf16 v[80:83], v[152:155], v[200:203], v[80:83]
	v_mfma_f32_16x16x32_bf16 v[108:111], v[156:159], v[172:175], v[108:111]
	v_mfma_f32_16x16x32_bf16 v[100:103], v[164:167], v[172:175], v[100:103]
	v_mfma_f32_16x16x32_bf16 v[92:95], v[156:159], v[180:183], v[92:95]
	v_mfma_f32_16x16x32_bf16 v[84:87], v[164:167], v[180:183], v[84:87]
	v_mfma_f32_16x16x32_bf16 v[76:79], v[156:159], v[188:191], v[76:79]
	v_mfma_f32_16x16x32_bf16 v[72:75], v[164:167], v[188:191], v[72:75]
	v_mfma_f32_16x16x32_bf16 v[68:71], v[156:159], v[196:199], v[68:71]
	v_mfma_f32_16x16x32_bf16 v[64:67], v[164:167], v[196:199], v[64:67]
	v_mfma_f32_16x16x32_bf16 v[108:111], v[160:163], v[176:179], v[108:111]
	v_mfma_f32_16x16x32_bf16 v[100:103], v[168:171], v[176:179], v[100:103]
	v_mfma_f32_16x16x32_bf16 v[92:95], v[160:163], v[184:187], v[92:95]
	v_mfma_f32_16x16x32_bf16 v[84:87], v[168:171], v[184:187], v[84:87]
	v_mfma_f32_16x16x32_bf16 v[76:79], v[160:163], v[192:195], v[76:79]
	v_mfma_f32_16x16x32_bf16 v[72:75], v[168:171], v[192:195], v[72:75]
	v_mfma_f32_16x16x32_bf16 v[68:71], v[160:163], v[200:203], v[68:71]
	v_mfma_f32_16x16x32_bf16 v[64:67], v[168:171], v[200:203], v[64:67]
	s_setprio 0
	s_barrier
	s_add_i32 s28, s29, s14
	v_lshl_add_u64 v[204:205], s[10:11], 0, v[128:129]
	s_mov_b32 m0, s28
	ds_read_b128 v[172:175], v139 offset:16384
	ds_read_b128 v[176:179], v139 offset:17408
	ds_read_b128 v[180:183], v139 offset:18432
	ds_read_b128 v[184:187], v139 offset:19456
	ds_read_b128 v[188:191], v139 offset:20480
	ds_read_b128 v[192:195], v139 offset:21504
	ds_read_b128 v[196:199], v139 offset:22528
	ds_read_b128 v[200:203], v139 offset:23552
	global_load_lds_dwordx4 v[204:205], off
	s_add_i32 m0, s28, 0x2000
	s_add_u32 s28, s10, 0x80000
	v_lshl_add_u64 v[206:207], s[10:11], 0, v[130:131]
	s_addc_u32 s29, s11, 0
	s_add_i32 s27, s27, s14
	global_load_lds_dwordx4 v[206:207], off
	v_lshl_add_u64 v[208:209], s[28:29], 0, v[128:129]
	s_mov_b32 m0, s27
	v_lshl_add_u64 v[210:211], s[12:13], 0, v[130:131]
	global_load_lds_dwordx4 v[208:209], off
	v_lshl_add_u64 v[208:209], s[28:29], 0, v[130:131]
	s_add_i32 m0, s27, 0x2000
	s_nop 0
	global_load_lds_dwordx4 v[208:209], off
	v_lshl_add_u64 v[208:209], s[12:13], 0, v[128:129]
	s_mov_b32 m0, s15
	s_nop 0
	global_load_lds_dwordx4 v[208:209], off
	s_mov_b32 m0, s16
	s_nop 0
	global_load_lds_dwordx4 v[210:211], off
	s_waitcnt vmcnt(8)
	s_waitcnt lgkmcnt(0)
	s_barrier
; #define PG8_STAGE(bufoff, gbase, voff) do { _Pragma("unroll") for (int _i = 0; _i < 2; ++_i) \
;         __builtin_amdgcn_global_load_lds((const unsigned*)((const char*)(gbase) + (voff)[_i]), (PG8_LAS unsigned*)(lds + (bufoff) + ldsw + _i * 8192), 16, 0, 0); } while (0)
; #define PG8_LDA(dst, b, h) do { _Pragma("unroll") for (int m = 0; m < 4; ++m) _Pragma("unroll") for (int k = 0; k < 2; ++k) dst[m][k] = *(const PG8_LAS bf16x8*)(lds + PG8_SA(b, h) + aoff + m * 2048 + k * 1024); } while (0)
; #define PG8_LDB(dst, b, h) do { _Pragma("unroll") for (int n = 0; n < 2; ++n) _Pragma("unroll") for (int k = 0; k < 2; ++k) dst[n][k] = *(const PG8_LAS bf16x8*)(lds + PG8_SB(b, h) + boff + n * 2048 + k * 1024); } while (0)
; #define PG8_MMA(ai, bj, At, Bt) do { __builtin_amdgcn_s_setprio(1); _Pragma("unroll") for (int m = 0; m < 4; ++m) _Pragma("unroll") for (int n = 0; n < 2; ++n) _Pragma("unroll") for (int k = 0; k < 2; ++k) \
;         acc[ai][bj][m][n] = __builtin_amdgcn_mfma_f32_16x16x32_bf16(Bt[n][k], At[m][k], acc[ai][bj][m][n], 0, 0, 0); __builtin_amdgcn_s_setprio(0); } while (0)
; #define PG8_WAIT_V(n) asm volatile("s_waitcnt vmcnt(" #n ")" ::: "memory")
; #define PG8_WAIT_L(n) asm volatile("s_waitcnt lgkmcnt(" #n ")" ::: "memory")
; #define PG8_BAR __builtin_amdgcn_s_barrier()
; #define PG8_SCHED __builtin_amdgcn_sched_barrier(0)
; template <class Epi, class Sched, bool ALIGN_EPI = false, bool SP2 = false>
; __device__ __forceinline__ void gemm_phase(PG8_LAS unsigned char* lds, const Gemm g, const Sched& S, const Epi& E) {
;     ...
;             PG8_LDA(At, 0, 1); PG8_STAGE(PG8_SB(0, 0), b2, voffB); PG8_STAGE(PG8_SB(0, 1), b2 + hstep, voffB); PG8_STAGE(PG8_SA(0, 0), a2, voffA);
;             PG8_WAIT_V(8); PG8_WAIT_L(0); PG8_BAR; PG8_MMA(1, 0, At, B0); PG8_MMA(1, 1, At, B1); PG8_BAR; PG8_SCHED;
;             PG8_LDB(B0, 1, 0); PG8_LDB(B1, 1, 1); PG8_SCHED; PG8_LDA(At, 1, 0); PG8_STAGE(PG8_SA(0, 1), a2 + hstep, voffA);
;             PG8_WAIT_V(8); PG8_WAIT_L(0); PG8_BAR; PG8_MMA(0, 0, At, B0); PG8_MMA(0, 1, At, B1); PG8_BAR; PG8_SCHED;
;             PG8_LDA(At, 1, 1); PG8_STAGE(PG8_SB(1, 0), b3, voffB); PG8_STAGE(PG8_SB(1, 1), b3 + hstep, voffB); PG8_STAGE(PG8_SA(1, 0), a3, voffA);
	s_setprio 1
	v_mfma_f32_16x16x32_bf16 v[60:63], v[140:143], v[172:175], v[60:63]
	v_mfma_f32_16x16x32_bf16 v[56:59], v[148:151], v[172:175], v[56:59]
	v_mfma_f32_16x16x32_bf16 v[52:55], v[140:143], v[180:183], v[52:55]
	v_mfma_f32_16x16x32_bf16 v[48:51], v[148:151], v[180:183], v[48:51]
	v_mfma_f32_16x16x32_bf16 v[36:39], v[140:143], v[188:191], v[36:39]
	v_mfma_f32_16x16x32_bf16 v[32:35], v[148:151], v[188:191], v[32:35]
	v_mfma_f32_16x16x32_bf16 v[20:23], v[140:143], v[196:199], v[20:23]
	v_mfma_f32_16x16x32_bf16 v[16:19], v[148:151], v[196:199], v[16:19]
	v_mfma_f32_16x16x32_bf16 v[60:63], v[144:147], v[176:179], v[60:63]
	v_mfma_f32_16x16x32_bf16 v[56:59], v[152:155], v[176:179], v[56:59]
	v_mfma_f32_16x16x32_bf16 v[52:55], v[144:147], v[184:187], v[52:55]
	v_mfma_f32_16x16x32_bf16 v[48:51], v[152:155], v[184:187], v[48:51]
	v_mfma_f32_16x16x32_bf16 v[36:39], v[144:147], v[192:195], v[36:39]
	v_mfma_f32_16x16x32_bf16 v[32:35], v[152:155], v[192:195], v[32:35]
	v_mfma_f32_16x16x32_bf16 v[20:23], v[144:147], v[200:203], v[20:23]
	v_mfma_f32_16x16x32_bf16 v[16:19], v[152:155], v[200:203], v[16:19]
	v_mfma_f32_16x16x32_bf16 v[44:47], v[156:159], v[172:175], v[44:47]
	v_mfma_f32_16x16x32_bf16 v[40:43], v[164:167], v[172:175], v[40:43]
	v_mfma_f32_16x16x32_bf16 v[28:31], v[156:159], v[180:183], v[28:31]
	v_mfma_f32_16x16x32_bf16 v[24:27], v[164:167], v[180:183], v[24:27]
	v_mfma_f32_16x16x32_bf16 v[12:15], v[156:159], v[188:191], v[12:15]
	v_mfma_f32_16x16x32_bf16 v[8:11], v[164:167], v[188:191], v[8:11]
	v_mfma_f32_16x16x32_bf16 v[4:7], v[156:159], v[196:199], v[4:7]
	v_mfma_f32_16x16x32_bf16 v[0:3], v[164:167], v[196:199], v[0:3]
	v_mfma_f32_16x16x32_bf16 v[44:47], v[160:163], v[176:179], v[44:47]
	v_mfma_f32_16x16x32_bf16 v[40:43], v[168:171], v[176:179], v[40:43]
	v_mfma_f32_16x16x32_bf16 v[28:31], v[160:163], v[184:187], v[28:31]
	v_mfma_f32_16x16x32_bf16 v[24:27], v[168:171], v[184:187], v[24:27]
	v_mfma_f32_16x16x32_bf16 v[12:15], v[160:163], v[192:195], v[12:15]
	v_mfma_f32_16x16x32_bf16 v[8:11], v[168:171], v[192:195], v[8:11]
	v_mfma_f32_16x16x32_bf16 v[4:7], v[160:163], v[200:203], v[4:7]
	v_mfma_f32_16x16x32_bf16 v[0:3], v[168:171], v[200:203], v[0:3]
	s_setprio 0
	s_barrier
	s_add_i32 s27, 0, 0x18000
	s_add_i32 s28, 0, 0x1c000
	v_add_u32_e32 v152, s27, v138
	v_add_u32_e32 v168, s28, v138
	ds_read_b128 v[140:143], v152
	ds_read_b128 v[144:147], v152 offset:1024
	ds_read_b128 v[148:151], v152 offset:2048
	ds_read_b128 v[152:155], v152 offset:3072
	ds_read_b128 v[156:159], v168
	ds_read_b128 v[160:163], v168 offset:1024
	ds_read_b128 v[164:167], v168 offset:2048
	ds_read_b128 v[168:171], v168 offset:3072
	s_add_u32 s12, s12, 0x80000
	s_addc_u32 s13, s13, 0
	s_mov_b32 m0, s17
	v_lshl_add_u64 v[212:213], s[12:13], 0, v[128:129]
	ds_read_b128 v[172:175], v139 offset:32768
	ds_read_b128 v[176:179], v139 offset:33792
	ds_read_b128 v[180:183], v139 offset:34816
	ds_read_b128 v[184:187], v139 offset:35840
	ds_read_b128 v[188:191], v139 offset:36864
	ds_read_b128 v[192:195], v139 offset:37888
	ds_read_b128 v[196:199], v139 offset:38912
	ds_read_b128 v[200:203], v139 offset:39936
	global_load_lds_dwordx4 v[212:213], off
	v_lshl_add_u64 v[212:213], s[12:13], 0, v[130:131]
	s_mov_b32 m0, s18
	s_nop 0
	global_load_lds_dwordx4 v[212:213], off
	s_waitcnt vmcnt(8)
	s_waitcnt lgkmcnt(0)
	s_barrier
	s_setprio 1
	v_mfma_f32_16x16x32_bf16 v[124:127], v[140:143], v[172:175], v[124:127]
	v_mfma_f32_16x16x32_bf16 v[120:123], v[148:151], v[172:175], v[120:123]
	v_mfma_f32_16x16x32_bf16 v[116:119], v[140:143], v[180:183], v[116:119]
	v_mfma_f32_16x16x32_bf16 v[112:115], v[148:151], v[180:183], v[112:115]
	v_mfma_f32_16x16x32_bf16 v[104:107], v[140:143], v[188:191], v[104:107]
	v_mfma_f32_16x16x32_bf16 v[96:99], v[148:151], v[188:191], v[96:99]
	v_mfma_f32_16x16x32_bf16 v[88:91], v[140:143], v[196:199], v[88:91]
	v_mfma_f32_16x16x32_bf16 v[80:83], v[148:151], v[196:199], v[80:83]
	v_mfma_f32_16x16x32_bf16 v[124:127], v[144:147], v[176:179], v[124:127]
	v_mfma_f32_16x16x32_bf16 v[120:123], v[152:155], v[176:179], v[120:123]
	v_mfma_f32_16x16x32_bf16 v[116:119], v[144:147], v[184:187], v[116:119]
	v_mfma_f32_16x16x32_bf16 v[112:115], v[152:155], v[184:187], v[112:115]
	v_mfma_f32_16x16x32_bf16 v[104:107], v[144:147], v[192:195], v[104:107]
	v_mfma_f32_16x16x32_bf16 v[96:99], v[152:155], v[192:195], v[96:99]
	v_mfma_f32_16x16x32_bf16 v[88:91], v[144:147], v[200:203], v[88:91]
	v_mfma_f32_16x16x32_bf16 v[80:83], v[152:155], v[200:203], v[80:83]
	v_mfma_f32_16x16x32_bf16 v[108:111], v[156:159], v[172:175], v[108:111]
	v_mfma_f32_16x16x32_bf16 v[100:103], v[164:167], v[172:175], v[100:103]
	v_mfma_f32_16x16x32_bf16 v[92:95], v[156:159], v[180:183], v[92:95]
	v_mfma_f32_16x16x32_bf16 v[84:87], v[164:167], v[180:183], v[84:87]
	v_mfma_f32_16x16x32_bf16 v[76:79], v[156:159], v[188:191], v[76:79]
	v_mfma_f32_16x16x32_bf16 v[72:75], v[164:167], v[188:191], v[72:75]
	v_mfma_f32_16x16x32_bf16 v[68:71], v[156:159], v[196:199], v[68:71]
	v_mfma_f32_16x16x32_bf16 v[64:67], v[164:167], v[196:199], v[64:67]
	v_mfma_f32_16x16x32_bf16 v[108:111], v[160:163], v[176:179], v[108:111]
	v_mfma_f32_16x16x32_bf16 v[100:103], v[168:171], v[176:179], v[100:103]
	v_mfma_f32_16x16x32_bf16 v[92:95], v[160:163], v[184:187], v[92:95]
	v_mfma_f32_16x16x32_bf16 v[84:87], v[168:171], v[184:187], v[84:87]
	v_mfma_f32_16x16x32_bf16 v[76:79], v[160:163], v[192:195], v[76:79]
	v_mfma_f32_16x16x32_bf16 v[72:75], v[168:171], v[192:195], v[72:75]
	v_mfma_f32_16x16x32_bf16 v[68:71], v[160:163], v[200:203], v[68:71]
	v_mfma_f32_16x16x32_bf16 v[64:67], v[168:171], v[200:203], v[64:67]
	s_setprio 0
	s_barrier
; #define PG8_STAGE(bufoff, gbase, voff) do { _Pragma("unroll") for (int _i = 0; _i < 2; ++_i) \
;         __builtin_amdgcn_global_load_lds((const unsigned*)((const char*)(gbase) + (voff)[_i]), (PG8_LAS unsigned*)(lds + (bufoff) + ldsw + _i * 8192), 16, 0, 0); } while (0)
; #define PG8_LDA(dst, b, h) do { _Pragma("unroll") for (int m = 0; m < 4; ++m) _Pragma("unroll") for (int k = 0; k < 2; ++k) dst[m][k] = *(const PG8_LAS bf16x8*)(lds + PG8_SA(b, h) + aoff + m * 2048 + k * 1024); } while (0)
; #define PG8_MMA(ai, bj, At, Bt) do { __builtin_amdgcn_s_setprio(1); _Pragma("unroll") for (int m = 0; m < 4; ++m) _Pragma("unroll") for (int n = 0; n < 2; ++n) _Pragma("unroll") for (int k = 0; k < 2; ++k) \
;         acc[ai][bj][m][n] = __builtin_amdgcn_mfma_f32_16x16x32_bf16(Bt[n][k], At[m][k], acc[ai][bj][m][n], 0, 0, 0); __builtin_amdgcn_s_setprio(0); } while (0)
; #define PG8_WAIT_V(n) asm volatile("s_waitcnt vmcnt(" #n ")" ::: "memory")
; #define PG8_WAIT_L(n) asm volatile("s_waitcnt lgkmcnt(" #n ")" ::: "memory")
; #define PG8_BAR __builtin_amdgcn_s_barrier()
; #define PG8_SCHED __builtin_amdgcn_sched_barrier(0)
; template <class Epi, class Sched, bool ALIGN_EPI = false, bool SP2 = false>
; __device__ __forceinline__ void gemm_phase(PG8_LAS unsigned char* lds, const Gemm g, const Sched& S, const Epi& E) {
;     ...
;             PG8_LDA(At, 1, 1); PG8_STAGE(PG8_SB(1, 0), b3, voffB); PG8_STAGE(PG8_SB(1, 1), b3 + hstep, voffB); PG8_STAGE(PG8_SA(1, 0), a3, voffA);
;             PG8_WAIT_V(8); PG8_WAIT_L(0); PG8_BAR; PG8_MMA(1, 0, At, B0); PG8_MMA(1, 1, At, B1); PG8_BAR; PG8_SCHED;
;     ...
;         if constexpr (ALIGN_EPI) { if (wr == 0) PG8_BAR; }
	s_add_i32 s12, s27, s14
	v_lshl_add_u64 v[204:205], v[204:205], 0, s[76:77]
	s_mov_b32 m0, s12
	ds_read_b128 v[172:175], v139 offset:49152
	ds_read_b128 v[176:179], v139 offset:50176
	ds_read_b128 v[180:183], v139 offset:51200
	ds_read_b128 v[184:187], v139 offset:52224
	ds_read_b128 v[188:191], v139 offset:53248
	ds_read_b128 v[192:195], v139 offset:54272
	ds_read_b128 v[196:199], v139 offset:55296
	ds_read_b128 v[200:203], v139 offset:56320
	global_load_lds_dwordx4 v[204:205], off
	s_add_i32 m0, s12, 0x2000
	s_add_u32 s10, s10, 0x80080
	v_lshl_add_u64 v[204:205], v[206:207], 0, s[76:77]
	s_addc_u32 s11, s11, 0
	s_add_i32 s12, s28, s14
	global_load_lds_dwordx4 v[204:205], off
	v_lshl_add_u64 v[204:205], s[10:11], 0, v[128:129]
	s_mov_b32 m0, s12
	s_nop 0
	global_load_lds_dwordx4 v[204:205], off
	v_lshl_add_u64 v[204:205], s[10:11], 0, v[130:131]
	s_add_i32 m0, s12, 0x2000
	s_nop 0
	global_load_lds_dwordx4 v[204:205], off
	v_lshl_add_u64 v[204:205], v[208:209], 0, s[76:77]
	s_mov_b32 m0, s20
	s_nop 0
	global_load_lds_dwordx4 v[204:205], off
	v_lshl_add_u64 v[204:205], v[210:211], 0, s[76:77]
	s_mov_b32 m0, s21
	s_nop 0
	global_load_lds_dwordx4 v[204:205], off
	s_waitcnt vmcnt(8)
	s_waitcnt lgkmcnt(0)
	s_barrier
	s_setprio 1
	v_mfma_f32_16x16x32_bf16 v[60:63], v[140:143], v[172:175], v[60:63]
	v_mfma_f32_16x16x32_bf16 v[56:59], v[148:151], v[172:175], v[56:59]
	v_mfma_f32_16x16x32_bf16 v[52:55], v[140:143], v[180:183], v[52:55]
	v_mfma_f32_16x16x32_bf16 v[48:51], v[148:151], v[180:183], v[48:51]
	v_mfma_f32_16x16x32_bf16 v[36:39], v[140:143], v[188:191], v[36:39]
	v_mfma_f32_16x16x32_bf16 v[32:35], v[148:151], v[188:191], v[32:35]
	v_mfma_f32_16x16x32_bf16 v[20:23], v[140:143], v[196:199], v[20:23]
	v_mfma_f32_16x16x32_bf16 v[16:19], v[148:151], v[196:199], v[16:19]
	v_mfma_f32_16x16x32_bf16 v[60:63], v[144:147], v[176:179], v[60:63]
	v_mfma_f32_16x16x32_bf16 v[56:59], v[152:155], v[176:179], v[56:59]
	v_mfma_f32_16x16x32_bf16 v[52:55], v[144:147], v[184:187], v[52:55]
	v_mfma_f32_16x16x32_bf16 v[48:51], v[152:155], v[184:187], v[48:51]
	v_mfma_f32_16x16x32_bf16 v[36:39], v[144:147], v[192:195], v[36:39]
	v_mfma_f32_16x16x32_bf16 v[32:35], v[152:155], v[192:195], v[32:35]
	v_mfma_f32_16x16x32_bf16 v[20:23], v[144:147], v[200:203], v[20:23]
	v_mfma_f32_16x16x32_bf16 v[16:19], v[152:155], v[200:203], v[16:19]
	v_mfma_f32_16x16x32_bf16 v[44:47], v[156:159], v[172:175], v[44:47]
	v_mfma_f32_16x16x32_bf16 v[40:43], v[164:167], v[172:175], v[40:43]
	v_mfma_f32_16x16x32_bf16 v[28:31], v[156:159], v[180:183], v[28:31]
	v_mfma_f32_16x16x32_bf16 v[24:27], v[164:167], v[180:183], v[24:27]
	v_mfma_f32_16x16x32_bf16 v[12:15], v[156:159], v[188:191], v[12:15]
	v_mfma_f32_16x16x32_bf16 v[8:11], v[164:167], v[188:191], v[8:11]
	v_mfma_f32_16x16x32_bf16 v[4:7], v[156:159], v[196:199], v[4:7]
	v_mfma_f32_16x16x32_bf16 v[0:3], v[164:167], v[196:199], v[0:3]
	v_mfma_f32_16x16x32_bf16 v[44:47], v[160:163], v[176:179], v[44:47]
	v_mfma_f32_16x16x32_bf16 v[40:43], v[168:171], v[176:179], v[40:43]
	v_mfma_f32_16x16x32_bf16 v[28:31], v[160:163], v[184:187], v[28:31]
	v_mfma_f32_16x16x32_bf16 v[24:27], v[168:171], v[184:187], v[24:27]
	v_mfma_f32_16x16x32_bf16 v[12:15], v[160:163], v[192:195], v[12:15]
	v_mfma_f32_16x16x32_bf16 v[8:11], v[168:171], v[192:195], v[8:11]
	v_mfma_f32_16x16x32_bf16 v[4:7], v[160:163], v[200:203], v[4:7]
	v_mfma_f32_16x16x32_bf16 v[0:3], v[168:171], v[200:203], v[0:3]
	s_setprio 0
	s_barrier
	s_add_i32 s26, s26, 2
	s_add_u32 s8, s8, 0x100
	s_addc_u32 s9, s9, 0
	s_cmp_gt_u32 s26, 29
	s_cbranch_scc0 .LBB0_645
	s_cmpk_lt_u32 s1, 0x100
	s_cbranch_scc0 .LBB0_648
	s_barrier
